# attention softmax step: redundant self-max canonicalisations, +0 add and empty-asm s_nop pads removed (MFMA distances re-checked)
# speedup vs baseline: 1.0067x; 1.0067x over previous
; __device__ __forceinline__ float max3f(float a,float b,float c){float r;asm("v_max3_f32 %0, %1, %2, %3":"=v"(r):"v"(a),"v"(b),"v"(c));return r;}
; __device__ __forceinline__ float max2f(float a,float b){float r;asm("v_max_f32_e32 %0, %1, %2":"=v"(r):"v"(a),"v"(b));return r;}
; #define WAIT_BAR(N) asm volatile("s_waitcnt vmcnt(" #N ") lgkmcnt(0)\n\ts_barrier":::"memory")
;   #define DMA_K(t,slot) glds16(ksrc+(long)KROW(t)*PK,(unsigned)__builtin_amdgcn_readfirstlane(kdst+(slot)))
;   #define DMA_V(t,slot) do{ glds16(vsrc+(long)KROW(t)*PV,(unsigned)__builtin_amdgcn_readfirstlane(vdst+2*(slot))); if(MODE==2)glds16(vsrc+(long)KROW(t)*PV+64,(unsigned)__builtin_amdgcn_readfirstlane(vdst+2*(slot)+SLOTB)); }while(0)
;   #define CMASK(P0,P1,t) do{ if(MODE==1&&(t)>=4)na_apply(P0,P1,mf,na_rowok((t),nabase,nar)); }while(0)
;   #define ROT() do{sl_prev=sl_cur;sl_cur=sl_next;sl_next=(sl_next==(NSLOT-1)*SLOTB)?0:sl_next+SLOTB;}while(0)
; __device__ __forceinline__ float rowmax(const f32x16&p0,const f32x16&p1){
;   float a=max3f(p0[0],p0[1],p1[0]),b=max3f(p0[2],p0[3],p1[1]);a=max3f(a,p1[2],p1[3]);
;   #pragma unroll
;   for(int r=4;r<16;r+=4){a=max3f(a,p0[r],p0[r+1]);b=max3f(b,p0[r+2],p0[r+3]);a=max3f(a,p1[r],p1[r+1]);b=max3f(b,p1[r+2],p1[r+3]);}
;   const float m=max2f(a,b);
;   auto rr=__builtin_amdgcn_permlane32_swap(__float_as_uint(m),__float_as_uint(m),false,false);
;   return max2f(__uint_as_float(rr[0]),__uint_as_float(rr[1]));
; }
; template<int MODE,int THRL> __device__ __forceinline__ void attn_unit(const bf16*Qw0,int PQ,const bf16*__restrict__ Kh,int PK,const bf16*__restrict__ Vh,int PV,bf16*Ow0,int PO,int NT,int nabase,int nar0,const float*rpbh,char*shm,int&rot,bool pre,bool hasn,long dKn,long dVn){
;     ...
;   if(pre){WAIT_BAR(0);}else if(MODE==2){WAIT_BAR(4);}else{WAIT_BAR(3);}
;   qkt(pA0,pA1,Kbase+sl_cur,qr,negm,r32,hi);asm volatile("s_nop 15\n\ts_nop 7":"+v"(pA0),"+v"(pA1));CMASK(pA0,pA1,0);
;   START(pA0,pA1);
;   _Pragma("unroll") for(int r=0;r<16;++r)pA1[r]=__builtin_amdgcn_exp2f(pA1[r]);
;   WAIT_BAR(0);
;   DMA_K(3,sl_cur);DMA_V(1,sl_next);
;   ROT();
;   kload8(kf,kp0+sl_cur);
;   if(MODE==2){WAIT_BAR(3);}else{WAIT_BAR(2);}
.LBB0_326:
	v_lshlrev_b32_e32 v35, 10, v237
	v_lshlrev_b32_e32 v48, 4, v236
	v_add3_u32 v1, s14, v35, v48
	ds_read_b128 v[36:39], v1
	ds_read_b128 v[40:43], v1 offset:512
	s_lshl_b32 s12, s12, 2
	v_or_b32_e32 v244, v35, v48
	s_waitcnt vmcnt(3) lgkmcnt(1)
	v_mfma_f32_32x32x16_bf16 v[18:33], v[36:39], v[142:145], v[2:17]
	s_and_b32 s4, s3, 0x3fffffc0
	s_lshl_b32 s67, s4, 2
	s_add_i32 s4, s78, s14
	s_lshl_b32 s70, s62, 1
	v_lshl_add_u64 v[206:207], v[228:229], 0, s[48:49]
	s_add_i32 s67, s67, 0x12000
	v_lshl_or_b32 v240, v236, 2, s67
	s_waitcnt lgkmcnt(0)
	v_mfma_f32_32x32x16_bf16 v[2:17], v[40:43], v[142:145], v[2:17]
	ds_read_b128 v[36:39], v1 offset:2048
	ds_read_b128 v[40:43], v1 offset:2560
	s_waitcnt vmcnt(2) lgkmcnt(1)
	v_mfma_f32_32x32x16_bf16 v[18:33], v[36:39], v[138:141], v[18:33]
	s_waitcnt lgkmcnt(0)
	v_mfma_f32_32x32x16_bf16 v[2:17], v[40:43], v[138:141], v[2:17]
	ds_read_b128 v[36:39], v1 offset:4096
	ds_read_b128 v[40:43], v1 offset:4608
	s_waitcnt vmcnt(1) lgkmcnt(1)
	v_mfma_f32_32x32x16_bf16 v[18:33], v[36:39], v[134:137], v[18:33]
	ds_read_b128 v[36:39], v1 offset:6656
	ds_read_b128 v[44:47], v1 offset:6144
	v_med3_u32 v1, s12, 4, v232
	s_nop 0
	v_readfirstlane_b32 s80, v1
	v_lshlrev_b32_e32 v1, 1, v34
	v_and_b32_e32 v239, 32, v1
	v_lshlrev_b32_e32 v1, 4, v34
	s_waitcnt lgkmcnt(2)
	v_mfma_f32_32x32x16_bf16 v[2:17], v[40:43], v[134:137], v[2:17]
	s_lshl_b32 s15, s80, 6
	v_and_b32_e32 v1, 0xc0, v1
	v_lshl_or_b32 v1, v237, 8, v1
	v_or3_b32 v243, v239, v238, v1
	s_waitcnt vmcnt(0) lgkmcnt(0)
	v_mfma_f32_32x32x16_bf16 v[18:33], v[44:47], v[130:133], v[18:33]
	v_mfma_f32_32x32x16_bf16 v[2:17], v[36:39], v[130:133], v[2:17]
	s_nop 15
	s_nop 7
	s_nop 0
	v_max3_f32 v34, v18, v19, v2
	v_max3_f32 v35, v20, v21, v3
	s_nop 0
	v_max3_f32 v34, v34, v4, v5
	v_max3_f32 v35, v35, v24, v25
	s_nop 0
	v_max3_f32 v34, v34, v22, v23
	v_max3_f32 v35, v35, v8, v9
	s_nop 0
	v_max3_f32 v34, v34, v6, v7
	v_max3_f32 v35, v35, v28, v29
	s_nop 0
	v_max3_f32 v34, v34, v26, v27
	v_max3_f32 v35, v35, v12, v13
	s_nop 0
	v_max3_f32 v34, v34, v10, v11
	v_max3_f32 v35, v35, v32, v33
	s_nop 0
	v_max3_f32 v34, v34, v30, v31
	v_max3_f32 v35, v35, v16, v17
	s_nop 0
	v_max3_f32 v34, v34, v14, v15
	s_nop 0
	v_max_f32_e32 v34, v34, v35
	s_nop 0
	v_mov_b32_e32 v35, v34
	s_nop 1
	v_permlane32_swap_b32_e32 v34, v35
	v_max_f32_e32 v34, v34, v35
	s_nop 0
	v_add_f32_e32 v241, v0, v34
	v_sub_f32_e32 v18, v18, v34
	v_sub_f32_e32 v2, v2, v34
	v_sub_f32_e32 v19, v19, v34
	v_sub_f32_e32 v3, v3, v34
	v_sub_f32_e32 v20, v20, v34
	v_sub_f32_e32 v4, v4, v34
	v_sub_f32_e32 v21, v21, v34
	v_sub_f32_e32 v5, v5, v34
	v_sub_f32_e32 v22, v22, v34
	v_sub_f32_e32 v6, v6, v34
	v_sub_f32_e32 v23, v23, v34
	v_sub_f32_e32 v7, v7, v34
	v_sub_f32_e32 v24, v24, v34
	v_sub_f32_e32 v8, v8, v34
	v_sub_f32_e32 v25, v25, v34
	v_sub_f32_e32 v9, v9, v34
	v_sub_f32_e32 v26, v26, v34
	v_sub_f32_e32 v10, v10, v34
	v_sub_f32_e32 v27, v27, v34
	v_sub_f32_e32 v11, v11, v34
	v_sub_f32_e32 v28, v28, v34
	v_sub_f32_e32 v12, v12, v34
	v_sub_f32_e32 v29, v29, v34
	v_sub_f32_e32 v13, v13, v34
	v_sub_f32_e32 v30, v30, v34
	v_sub_f32_e32 v14, v14, v34
	v_sub_f32_e32 v31, v31, v34
	v_sub_f32_e32 v15, v15, v34
	v_sub_f32_e32 v32, v32, v34
	v_sub_f32_e32 v16, v16, v34
	v_sub_f32_e32 v33, v33, v34
	v_sub_f32_e32 v17, v17, v34
	s_nop 0
	v_xor_b32_e32 v34, 0x80000000, v241
	v_mov_b32_e32 v35, v34
	v_mov_b32_e32 v36, v34
	v_mov_b32_e32 v37, v34
	v_mov_b32_e32 v38, v34
	v_mov_b32_e32 v39, v34
	v_mov_b32_e32 v40, v34
	v_mov_b32_e32 v41, v34
	v_mov_b32_e32 v42, v34
	v_mov_b32_e32 v43, v34
	v_mov_b32_e32 v44, v34
	v_mov_b32_e32 v45, v34
	v_mov_b32_e32 v46, v34
	v_mov_b32_e32 v47, v34
	v_mov_b32_e32 v48, v34
	v_mov_b32_e32 v49, v34
	s_waitcnt vmcnt(0) lgkmcnt(0)
	s_barrier
	v_exp_f32_e32 v112, v2
	v_exp_f32_e32 v113, v3
	v_lshl_add_u64 v[2:3], v[214:215], 0, s[54:55]
	s_mov_b32 s5, m0
	s_mov_b32 m0, s4
	s_nop 0
	global_load_lds_dwordx4 v[2:3], off
	s_mov_b32 m0, s5
	s_add_i32 s4, s70, s79
	s_mov_b32 s5, m0
	s_mov_b32 m0, s4
	s_nop 0
	global_load_lds_dwordx4 v[206:207], off
	s_mov_b32 m0, s5
	v_add_u32_e32 v2, s62, v244
	v_exp_f32_e32 v50, v22
	v_exp_f32_e32 v51, v23
	v_exp_f32_e32 v70, v24
	v_exp_f32_e32 v71, v25
	v_exp_f32_e32 v72, v26
	v_exp_f32_e32 v73, v27
	v_exp_f32_e32 v74, v28
	v_exp_f32_e32 v75, v29
	v_exp_f32_e32 v92, v30
	v_exp_f32_e32 v93, v31
	v_exp_f32_e32 v94, v32
	v_exp_f32_e32 v95, v33
	v_exp_f32_e32 v116, v6
	v_exp_f32_e32 v117, v7
	v_exp_f32_e32 v146, v8
	v_exp_f32_e32 v147, v9
	v_exp_f32_e32 v148, v10
	v_exp_f32_e32 v149, v11
	v_exp_f32_e32 v150, v12
	v_exp_f32_e32 v151, v13
	v_exp_f32_e32 v152, v14
	v_exp_f32_e32 v153, v15
	v_exp_f32_e32 v154, v16
	v_exp_f32_e32 v155, v17
	ds_read_b128 v[6:9], v2
	ds_read_b128 v[10:13], v2 offset:512
	ds_read_b128 v[14:17], v2 offset:2048
	ds_read_b128 v[22:25], v2 offset:2560
	ds_read_b128 v[26:29], v2 offset:4096
	ds_read_b128 v[30:33], v2 offset:4608
	ds_read_b128 v[66:69], v2 offset:6144
	ds_read_b128 v[108:111], v2 offset:6656
	v_exp_f32_e32 v18, v18
	v_exp_f32_e32 v19, v19
	v_exp_f32_e32 v20, v20
	v_exp_f32_e32 v21, v21
	v_exp_f32_e32 v114, v4
	v_exp_f32_e32 v115, v5
	s_waitcnt vmcnt(2) lgkmcnt(0)
	s_barrier
	s_cmpk_lg_i32 s62, 0x4000
	s_cselect_b32 s57, s57, 0
	v_cmp_gt_u32_e64 s[4:5], 32, v234
	v_lshl_add_u32 v156, s14, 1, v243
	ds_read_b64_tr_b16 v[2:3], v156 offset:24576
	ds_read_b64_tr_b16 v[4:5], v156 offset:25088
	s_waitcnt lgkmcnt(9)
	v_mfma_f32_32x32x16_bf16 v[76:91], v[6:9], v[142:145], v[34:49]
	v_add_f32_e32 v52, v18, v19
	v_add_f32_e32 v52, v52, v20
	v_add_f32_e32 v52, v52, v21
	v_add_f32_e32 v52, v52, v50
	v_add_f32_e32 v52, v52, v51
	v_cvt_pk_bf16_f32 v126, v18, v19
	v_cvt_pk_bf16_f32 v127, v20, v21
	ds_read_b64_tr_b16 v[18:19], v156 offset:28672
	ds_read_b64_tr_b16 v[20:21], v156 offset:29184
	v_add_f32_e32 v6, v70, v52
	v_cvt_pk_bf16_f32 v128, v50, v51
	s_waitcnt lgkmcnt(10)
	v_mfma_f32_32x32x16_bf16 v[50:65], v[10:13], v[142:145], v[34:49]
	v_add_f32_e32 v6, v71, v6
	v_add_f32_e32 v6, v72, v6
	v_add_f32_e32 v6, v73, v6
	v_cvt_pk_bf16_f32 v129, v70, v71
	ds_read_b64_tr_b16 v[104:105], v156 offset:25600
	ds_read_b64_tr_b16 v[106:107], v156 offset:26112
	s_waitcnt lgkmcnt(11)
	v_mfma_f32_32x32x16_bf16 v[76:91], v[14:17], v[138:141], v[76:91]
	v_add_f32_e32 v6, v74, v6
	v_add_f32_e32 v6, v75, v6
	v_add_f32_e32 v6, v92, v6
	v_add_f32_e32 v6, v93, v6
	v_cvt_pk_bf16_f32 v122, v72, v73
	v_cvt_pk_bf16_f32 v123, v74, v75
	ds_read_b64_tr_b16 v[100:101], v156 offset:29696
	ds_read_b64_tr_b16 v[102:103], v156 offset:30208
	s_waitcnt lgkmcnt(12)
	v_mfma_f32_32x32x16_bf16 v[50:65], v[22:25], v[138:141], v[50:65]
	v_add_f32_e32 v6, v94, v6
	v_add_f32_e32 v6, v95, v6
	v_add_f32_e32 v6, v112, v6
	v_add_f32_e32 v6, v113, v6
	v_cvt_pk_bf16_f32 v124, v92, v93
	v_cvt_pk_bf16_f32 v125, v94, v95
	ds_read_b64_tr_b16 v[96:97], v156 offset:26624
	ds_read_b64_tr_b16 v[98:99], v156 offset:27136
	s_waitcnt lgkmcnt(13)
	v_mfma_f32_32x32x16_bf16 v[76:91], v[26:29], v[134:137], v[76:91]
	v_add_f32_e32 v6, v114, v6
	v_add_f32_e32 v6, v115, v6
	v_add_f32_e32 v6, v116, v6
	v_add_f32_e32 v6, v117, v6
	v_cvt_pk_bf16_f32 v118, v112, v113
	v_cvt_pk_bf16_f32 v119, v114, v115
	ds_read_b64_tr_b16 v[92:93], v156 offset:30720
	ds_read_b64_tr_b16 v[94:95], v156 offset:31232
	s_waitcnt lgkmcnt(14)
	v_mfma_f32_32x32x16_bf16 v[50:65], v[30:33], v[134:137], v[50:65]
	v_add_f32_e32 v6, v146, v6
	v_add_f32_e32 v6, v147, v6
	v_add_f32_e32 v6, v148, v6
	v_add_f32_e32 v6, v149, v6
	v_cvt_pk_bf16_f32 v120, v116, v117
	v_cvt_pk_bf16_f32 v121, v146, v147
	ds_read_b64_tr_b16 v[70:71], v156 offset:27648
	ds_read_b64_tr_b16 v[72:73], v156 offset:28160
	s_waitcnt lgkmcnt(14)
	v_mfma_f32_32x32x16_bf16 v[76:91], v[66:69], v[130:133], v[76:91]
	v_add_f32_e32 v6, v150, v6
	v_add_f32_e32 v6, v151, v6
	v_add_f32_e32 v6, v152, v6
	v_add_f32_e32 v6, v153, v6
	v_cvt_pk_bf16_f32 v114, v148, v149
	v_cvt_pk_bf16_f32 v115, v150, v151
	ds_read_b64_tr_b16 v[66:67], v156 offset:31744
	ds_read_b64_tr_b16 v[68:69], v156 offset:32256
	v_mfma_f32_32x32x16_bf16 v[50:65], v[108:111], v[130:133], v[50:65]
	v_add_f32_e32 v6, v154, v6
	v_add_f32_e32 v6, v155, v6
	v_cvt_pk_bf16_f32 v116, v152, v153
	v_cvt_pk_bf16_f32 v117, v154, v155
	s_nop 0
	v_add_f32_e32 v184, 0, v6
	v_mad_u64_u32 v[6:7], s[64:65], s15, v233, v[214:215]
	s_add_i32 s14, s62, s78
	s_mov_b32 s62, m0
	s_mov_b32 m0, s14
	s_nop 0
	global_load_lds_dwordx4 v[6:7], off
	s_mov_b32 m0, s62
	v_lshl_add_u64 v[6:7], v[228:229], 0, s[52:53]
	s_lshl_b32 s66, s57, 1
	s_add_i32 s14, s66, s79
	s_mov_b32 s62, m0
	s_mov_b32 m0, s14
	s_nop 0
	global_load_lds_dwordx4 v[6:7], off
	s_mov_b32 m0, s62
	v_max_f32_e32 v6, v76, v77
	v_max3_f32 v7, v78, v79, v51
	v_max3_f32 v6, v6, v50, v52
	v_max3_f32 v6, v6, v53, v80
	v_max3_f32 v7, v7, v82, v83
	v_max3_f32 v6, v6, v81, v54
	v_max3_f32 v7, v7, v56, v57
	v_max3_f32 v6, v6, v55, v84
	v_max3_f32 v7, v7, v86, v87
	v_max3_f32 v6, v6, v85, v58
	v_max3_f32 v7, v7, v60, v61
	v_max3_f32 v6, v6, v59, v88
	v_max3_f32 v7, v7, v90, v91
	v_max3_f32 v6, v6, v89, v62
	v_max3_f32 v7, v7, v64, v65
	v_max3_f32 v6, v6, v63, v7
	v_mov_b32_e32 v7, v6
	s_nop 1
	v_permlane32_swap_b32_e32 v6, v7
	v_max_f32_e32 v6, v6, v7
	v_cmp_lt_f32_e32 vcc, s43, v6
	s_cmp_lg_u64 vcc, 0
	s_cselect_b64 s[62:63], -1, 0
	s_cbranch_vccnz .LBB0_428

.LBB0_329:
	s_add_i32 s14, s15, 0xffffff00
	s_add_i32 s15, s57, 0x2000
	s_cmpk_lg_i32 s57, 0x4000
	s_cselect_b32 s67, s15, 0
	v_add_u32_e32 v96, s70, v243
	ds_read_b64_tr_b16 v[154:155], v96 offset:24576
	ds_read_b64_tr_b16 v[156:157], v96 offset:25088
	s_waitcnt lgkmcnt(9)
	v_mfma_f32_32x32x16_bf16 v[98:113], v[150:153], v[142:145], v[34:49]
	v_add_f32_e32 v66, v76, v77
	v_add_f32_e32 v66, v78, v66
	v_add_f32_e32 v66, v79, v66
	v_add_f32_e32 v66, v80, v66
	v_add_f32_e32 v66, v81, v66
	v_cvt_pk_bf16_f32 v126, v76, v77
	v_cvt_pk_bf16_f32 v127, v78, v79
	ds_read_b64_tr_b16 v[150:151], v96 offset:28672
	ds_read_b64_tr_b16 v[152:153], v96 offset:29184
	v_add_f32_e32 v66, v82, v66
	v_add_f32_e32 v66, v83, v66
	v_add_f32_e32 v66, v84, v66
	v_add_f32_e32 v92, v85, v66
	v_cvt_pk_bf16_f32 v128, v80, v81
	s_waitcnt lgkmcnt(10)
	v_mfma_f32_32x32x16_bf16 v[66:81], v[146:149], v[142:145], v[34:49]
	v_cvt_pk_bf16_f32 v129, v82, v83
	ds_read_b64_tr_b16 v[146:147], v96 offset:25600
	ds_read_b64_tr_b16 v[148:149], v96 offset:26112
	s_waitcnt lgkmcnt(11)
	v_mfma_f32_32x32x16_bf16 v[98:113], v[178:181], v[138:141], v[98:113]
	v_add_f32_e32 v82, v86, v92
	v_add_f32_e32 v82, v87, v82
	v_add_f32_e32 v82, v88, v82
	v_add_f32_e32 v82, v89, v82
	v_cvt_pk_bf16_f32 v122, v84, v85
	v_cvt_pk_bf16_f32 v123, v86, v87
	ds_read_b64_tr_b16 v[92:93], v96 offset:29696
	ds_read_b64_tr_b16 v[94:95], v96 offset:30208
	s_waitcnt lgkmcnt(12)
	v_mfma_f32_32x32x16_bf16 v[66:81], v[170:173], v[138:141], v[66:81]
	v_add_f32_e32 v82, v90, v82
	v_add_f32_e32 v82, v91, v82
	v_add_f32_e32 v82, v50, v82
	v_add_f32_e32 v82, v51, v82
	v_cvt_pk_bf16_f32 v124, v88, v89
	v_cvt_pk_bf16_f32 v125, v90, v91
	ds_read_b64_tr_b16 v[86:87], v96 offset:26624
	ds_read_b64_tr_b16 v[88:89], v96 offset:27136
	s_waitcnt lgkmcnt(13)
	v_mfma_f32_32x32x16_bf16 v[98:113], v[174:177], v[134:137], v[98:113]
	v_add_f32_e32 v82, v52, v82
	v_add_f32_e32 v82, v53, v82
	v_add_f32_e32 v82, v54, v82
	v_add_f32_e32 v90, v55, v82
	v_cvt_pk_bf16_f32 v118, v50, v51
	v_cvt_pk_bf16_f32 v119, v52, v53
	ds_read_b64_tr_b16 v[82:83], v96 offset:30720
	ds_read_b64_tr_b16 v[84:85], v96 offset:31232
	s_waitcnt lgkmcnt(14)
	v_mfma_f32_32x32x16_bf16 v[66:81], v[162:165], v[134:137], v[66:81]
	v_add_f32_e32 v50, v56, v90
	v_add_f32_e32 v50, v57, v50
	v_add_f32_e32 v50, v58, v50
	v_add_f32_e32 v50, v59, v50
	v_cvt_pk_bf16_f32 v120, v54, v55
	v_cvt_pk_bf16_f32 v121, v56, v57
	ds_read_b64_tr_b16 v[54:55], v96 offset:27648
	ds_read_b64_tr_b16 v[56:57], v96 offset:28160
	s_waitcnt lgkmcnt(14)
	v_mfma_f32_32x32x16_bf16 v[98:113], v[166:169], v[130:133], v[98:113]
	v_add_f32_e32 v50, v60, v50
	v_add_f32_e32 v50, v61, v50
	v_add_f32_e32 v50, v62, v50
	v_add_f32_e32 v90, v63, v50
	v_cvt_pk_bf16_f32 v114, v58, v59
	v_cvt_pk_bf16_f32 v115, v60, v61
	ds_read_b64_tr_b16 v[50:51], v96 offset:31744
	ds_read_b64_tr_b16 v[52:53], v96 offset:32256
	v_mfma_f32_32x32x16_bf16 v[66:81], v[158:161], v[130:133], v[66:81]
	v_add_f32_e32 v58, v64, v90
	v_add_f32_e32 v58, v65, v58
	v_cvt_pk_bf16_f32 v116, v62, v63
	v_cvt_pk_bf16_f32 v117, v64, v65
	s_add_i32 s15, s14, 0x140
	v_add_f32_e32 v184, v184, v58
	v_mad_u64_u32 v[58:59], s[62:63], s15, v233, v[214:215]
	s_add_i32 s15, s57, s78
	s_mov_b32 s57, m0
	s_mov_b32 m0, s15
	s_nop 0
	global_load_lds_dwordx4 v[58:59], off
	s_mov_b32 m0, s57
	v_lshl_add_u64 v[58:59], v[228:229], 0, s[54:55]
	s_lshl_b32 s15, s67, 1
	s_add_i32 s57, s15, s79
	s_mov_b32 s62, m0
	s_mov_b32 m0, s57
	s_nop 0
	global_load_lds_dwordx4 v[58:59], off
	s_mov_b32 m0, s62
	v_max_f32_e32 v58, v98, v99
	v_max3_f32 v59, v100, v101, v67
	v_max3_f32 v58, v58, v66, v68
	v_max3_f32 v58, v58, v69, v102
	v_max3_f32 v59, v59, v104, v105
	v_max3_f32 v58, v58, v103, v70
	v_max3_f32 v59, v59, v72, v73
	v_max3_f32 v58, v58, v71, v106
	v_max3_f32 v59, v59, v108, v109
	v_max3_f32 v58, v58, v107, v74
	v_max3_f32 v59, v59, v76, v77
	v_max3_f32 v58, v58, v75, v110
	v_max3_f32 v59, v59, v112, v113
	v_max3_f32 v58, v58, v111, v78
	v_max3_f32 v59, v59, v80, v81
	v_max3_f32 v58, v58, v79, v59
	v_mov_b32_e32 v59, v58
	s_nop 1
	v_permlane32_swap_b32_e32 v58, v59
	v_max_f32_e32 v58, v58, v59
	v_cmp_lt_f32_e32 vcc, s43, v58
	s_cmp_lg_u64 vcc, 0
	s_cselect_b64 s[62:63], -1, 0
	s_cbranch_vccnz .LBB0_431

; __device__ __forceinline__ void na_mfload(u32x4_t*mf,const unsigned*mfh,int t,int nabase,int r,int chalf,int lane){
;   const int dr=nabase+t-4-r+7; const u32x4_t*p=(const u32x4_t*)(mfh+(size_t)(((dr*2+chalf)*64+lane)*16));
;   #pragma unroll
;   for(int i=0;i<4;++i)mf[i]=p[i];
; }
.LBB0_332:
	s_ashr_i32 s72, s3, 7
	s_add_i32 s12, s72, s12
	s_max_i32 s3, s12, 4
	s_min_i32 s81, s3, 0x7c
	s_sub_i32 s57, s80, s12
	s_add_i32 s82, s81, 8
	s_add_i32 s12, s57, 0x1ffff9
	s_mul_i32 s13, s13, 0x1e000
	s_add_u32 s62, s33, s13
	v_lshlrev_b32_e32 v198, 4, v234
	s_addc_u32 s63, s39, 0
	s_and_b32 s73, s78, 0x400
	v_or_b32_e32 v50, s73, v198
	v_or_b32_e32 v245, 0x3800, v50
	v_add_u32_e32 v185, s66, v243
	ds_read_b64_tr_b16 v[170:171], v185 offset:24576
	ds_read_b64_tr_b16 v[172:173], v185 offset:25088
	s_waitcnt lgkmcnt(9)
	v_mfma_f32_32x32x16_bf16 v[82:97], v[58:61], v[142:145], v[34:49]
	v_add_f32_e32 v50, v98, v99
	v_add_f32_e32 v50, v100, v50
	v_add_f32_e32 v50, v101, v50
	v_add_f32_e32 v50, v102, v50
	v_add_f32_e32 v50, v103, v50
	v_cvt_pk_bf16_f32 v126, v98, v99
	v_cvt_pk_bf16_f32 v127, v100, v101
	ds_read_b64_tr_b16 v[166:167], v185 offset:28672
	ds_read_b64_tr_b16 v[168:169], v185 offset:29184
	v_add_f32_e32 v50, v104, v50
	v_add_f32_e32 v50, v105, v50
	v_add_f32_e32 v50, v106, v50
	v_add_f32_e32 v98, v107, v50
	s_waitcnt lgkmcnt(10)
	v_mfma_f32_32x32x16_bf16 v[50:65], v[162:165], v[142:145], v[34:49]
	v_cvt_pk_bf16_f32 v128, v102, v103
	v_cvt_pk_bf16_f32 v129, v104, v105
	ds_read_b64_tr_b16 v[162:163], v185 offset:25600
	ds_read_b64_tr_b16 v[164:165], v185 offset:26112
	s_waitcnt lgkmcnt(11)
	v_mfma_f32_32x32x16_bf16 v[82:97], v[178:181], v[138:141], v[82:97]
	v_add_f32_e32 v98, v108, v98
	v_add_f32_e32 v98, v109, v98
	v_add_f32_e32 v98, v110, v98
	v_add_f32_e32 v98, v111, v98
	v_cvt_pk_bf16_f32 v122, v106, v107
	v_cvt_pk_bf16_f32 v123, v108, v109
	ds_read_b64_tr_b16 v[106:107], v185 offset:29696
	ds_read_b64_tr_b16 v[108:109], v185 offset:30208
	s_waitcnt lgkmcnt(12)
	v_mfma_f32_32x32x16_bf16 v[50:65], v[158:161], v[138:141], v[50:65]
	v_add_f32_e32 v98, v112, v98
	v_add_f32_e32 v98, v113, v98
	v_add_f32_e32 v98, v66, v98
	v_add_f32_e32 v98, v67, v98
	v_cvt_pk_bf16_f32 v124, v110, v111
	v_cvt_pk_bf16_f32 v125, v112, v113
	ds_read_b64_tr_b16 v[102:103], v185 offset:26624
	ds_read_b64_tr_b16 v[104:105], v185 offset:27136
	s_waitcnt lgkmcnt(13)
	v_mfma_f32_32x32x16_bf16 v[82:97], v[174:177], v[134:137], v[82:97]
	v_add_f32_e32 v98, v68, v98
	v_add_f32_e32 v98, v69, v98
	v_add_f32_e32 v98, v70, v98
	v_add_f32_e32 v110, v71, v98
	v_cvt_pk_bf16_f32 v118, v66, v67
	v_cvt_pk_bf16_f32 v119, v68, v69
	ds_read_b64_tr_b16 v[98:99], v185 offset:30720
	ds_read_b64_tr_b16 v[100:101], v185 offset:31232
	s_waitcnt lgkmcnt(14)
	v_mfma_f32_32x32x16_bf16 v[50:65], v[150:153], v[134:137], v[50:65]
	v_add_f32_e32 v66, v72, v110
	v_add_f32_e32 v66, v73, v66
	v_add_f32_e32 v66, v74, v66
	v_add_f32_e32 v66, v75, v66
	v_cvt_pk_bf16_f32 v120, v70, v71
	v_cvt_pk_bf16_f32 v121, v72, v73
	ds_read_b64_tr_b16 v[70:71], v185 offset:27648
	ds_read_b64_tr_b16 v[72:73], v185 offset:28160
	s_waitcnt lgkmcnt(14)
	v_mfma_f32_32x32x16_bf16 v[82:97], v[154:157], v[130:133], v[82:97]
	v_add_f32_e32 v66, v76, v66
	v_add_f32_e32 v66, v77, v66
	v_add_f32_e32 v66, v78, v66
	v_add_f32_e32 v110, v79, v66
	v_cvt_pk_bf16_f32 v114, v74, v75
	v_cvt_pk_bf16_f32 v115, v76, v77
	ds_read_b64_tr_b16 v[66:67], v185 offset:31744
	ds_read_b64_tr_b16 v[68:69], v185 offset:32256
	v_mfma_f32_32x32x16_bf16 v[50:65], v[146:149], v[130:133], v[50:65]
	v_add_f32_e32 v74, v80, v110
	v_add_f32_e32 v74, v81, v74
	v_cvt_pk_bf16_f32 v116, v78, v79
	v_cvt_pk_bf16_f32 v117, v80, v81
	s_cmp_gt_u32 s3, s80
	s_cselect_b64 s[64:65], -1, 0
	s_cmp_ge_u32 s80, s82
	s_cselect_b64 s[70:71], -1, 0
	s_or_b64 s[64:65], s[64:65], s[70:71]
	s_and_b64 vcc, exec, s[64:65]
	s_cbranch_vccnz .LBB0_334
	s_lshl_b32 s13, s12, 11
	s_addk_i32 s13, 0x1800
	v_add_u32_e32 v76, s13, v245
	v_ashrrev_i32_e32 v77, 31, v76
	v_lshl_add_u64 v[76:77], v[76:77], 2, s[62:63]
	global_load_dwordx4 v[146:149], v[76:77], off offset:48
	global_load_dwordx4 v[154:157], v[76:77], off offset:32
	global_load_dwordx4 v[150:153], v[76:77], off offset:16
	global_load_dwordx4 v[158:161], v[76:77], off
.LBB0_334:
	s_add_i32 s13, s67, 0x2000
	s_cmpk_lg_i32 s67, 0x4000
	s_cselect_b32 s86, s13, 0
	s_add_i32 s13, s14, 0x180
	v_add_f32_e32 v199, v184, v74
	v_mad_u64_u32 v[74:75], s[70:71], s13, v233, v[214:215]
	s_add_i32 s13, s67, s78
	s_mov_b32 s66, m0
	s_mov_b32 m0, s13
	s_nop 0
	global_load_lds_dwordx4 v[74:75], off
	s_mov_b32 m0, s66
	s_mul_i32 s66, s80, 0x48000
	s_mov_b32 s67, s7
	v_lshl_add_u64 v[74:75], v[182:183], 0, s[66:67]
	v_lshl_add_u64 v[230:231], v[74:75], 0, s[10:11]
	v_max_f32_e32 v74, v82, v83
	v_max3_f32 v75, v84, v85, v51
	v_max3_f32 v74, v74, v50, v52
	v_max3_f32 v74, v74, v53, v86
	v_max3_f32 v75, v75, v88, v89
	v_max3_f32 v74, v74, v87, v54
	v_max3_f32 v75, v75, v56, v57
	v_max3_f32 v74, v74, v55, v90
	v_max3_f32 v75, v75, v92, v93
	v_max3_f32 v74, v74, v91, v58
	v_max3_f32 v75, v75, v60, v61
	v_max3_f32 v74, v74, v59, v94
	v_max3_f32 v75, v75, v96, v97
	v_max3_f32 v74, v74, v95, v62
	v_max3_f32 v75, v75, v64, v65
	v_max3_f32 v74, v74, v63, v75
	v_mov_b32_e32 v75, v74
	s_nop 1
	v_permlane32_swap_b32_e32 v74, v75
	s_lshl_b32 s13, s86, 1
	v_max_f32_e32 v74, v74, v75
	s_add_i32 s13, s13, s79
	s_mov_b32 s66, m0
	s_mov_b32 m0, s13
	s_nop 0
	global_load_lds_dwordx4 v[230:231], off
	s_mov_b32 m0, s66
	v_cmp_lt_f32_e32 vcc, s43, v74
	s_cmp_lg_u64 vcc, 0
	s_cselect_b64 s[66:67], -1, 0
	s_cbranch_vccnz .LBB0_434

.LBB0_344:
	s_add_i32 s15, s86, 0x2000
	s_cmpk_lg_i32 s86, 0x4000
	s_cselect_b32 s15, s15, 0
	s_add_i32 s64, s14, 0x1c0
	v_mad_u64_u32 v[98:99], s[64:65], s64, v233, v[214:215]
	s_add_i32 s64, s86, s78
	s_mov_b32 s65, m0
	s_mov_b32 m0, s64
	s_nop 0
	global_load_lds_dwordx4 v[98:99], off
	s_mov_b32 m0, s65
	s_mul_i32 s64, s57, 0x48000
	s_mov_b32 s65, s7
	v_lshl_add_u64 v[98:99], v[228:229], 0, s[64:65]
	s_lshl_b32 s57, s15, 1
	s_add_i32 s57, s57, s79
	s_mov_b32 s64, m0
	s_mov_b32 m0, s57
	s_nop 0
	global_load_lds_dwordx4 v[98:99], off
	s_mov_b32 m0, s64
	v_max_f32_e32 v98, v66, v67
	v_max3_f32 v99, v68, v69, v51
	v_max3_f32 v98, v98, v50, v52
	v_max3_f32 v98, v98, v53, v70
	v_max3_f32 v99, v99, v72, v73
	v_max3_f32 v98, v98, v71, v54
	v_max3_f32 v99, v99, v56, v57
	v_max3_f32 v98, v98, v55, v74
	v_max3_f32 v99, v99, v76, v77
	v_max3_f32 v98, v98, v75, v58
	v_max3_f32 v99, v99, v60, v61
	v_max3_f32 v98, v98, v59, v78
	v_max3_f32 v99, v99, v80, v81
	v_max3_f32 v98, v98, v79, v62
	v_max3_f32 v99, v99, v64, v65
	v_max3_f32 v98, v98, v63, v99
	v_mov_b32_e32 v99, v98
	s_nop 1
	v_permlane32_swap_b32_e32 v98, v99
	v_max_f32_e32 v98, v98, v99
	v_cmp_lt_f32_e32 vcc, s43, v98
	s_cmp_lg_u64 vcc, 0
	v_add_f32_e32 v220, v199, v182
	s_cselect_b64 s[64:65], -1, 0
	s_cbranch_vccnz .LBB0_437

.LBB0_355:
	v_lshl_add_u64 v[216:217], v[210:211], 0, s[64:65]
	s_mov_b64 s[70:71], 0x120000
	v_lshl_add_u64 v[82:83], v[216:217], 0, s[70:71]
	v_lshl_add_u64 v[218:219], v[212:213], 0, s[64:65]
	s_add_i32 s70, s15, s78
	s_mov_b32 s71, m0
	s_mov_b32 m0, s70
	s_nop 0
	global_load_lds_dwordx4 v[82:83], off
	s_mov_b32 m0, s71
	v_lshl_add_u64 v[82:83], v[218:219], 0, s[52:53]
	s_lshl_b32 s86, s84, 1
	s_add_i32 s70, s86, s79
	s_mov_b32 s71, m0
	s_mov_b32 m0, s70
	s_nop 0
	global_load_lds_dwordx4 v[82:83], off
	s_mov_b32 m0, s71
	v_max_f32_e32 v82, v66, v67
	v_max3_f32 v83, v68, v69, v51
	v_max3_f32 v82, v82, v50, v52
	v_max3_f32 v82, v82, v53, v70
	v_max3_f32 v83, v83, v72, v73
	v_max3_f32 v82, v82, v71, v54
	v_max3_f32 v83, v83, v56, v57
	v_max3_f32 v82, v82, v55, v74
	v_max3_f32 v83, v83, v76, v77
	v_max3_f32 v82, v82, v75, v58
	v_max3_f32 v83, v83, v60, v61
	v_max3_f32 v82, v82, v59, v78
	v_max3_f32 v83, v83, v80, v81
	v_max3_f32 v82, v82, v79, v62
	v_max3_f32 v83, v83, v64, v65
	v_max3_f32 v82, v82, v63, v83
	v_mov_b32_e32 v83, v82
	s_nop 1
	v_permlane32_swap_b32_e32 v82, v83
	v_max_f32_e32 v82, v82, v83
	v_cmp_lt_f32_e32 vcc, s43, v82
	s_cmp_lg_u64 vcc, 0
	v_add_f32_e32 v209, v220, v178
	s_cselect_b64 s[70:71], -1, 0
	s_cbranch_vccnz .LBB0_370

.LBB0_365:
	s_add_i32 s15, s84, 0x2000
	s_cmpk_lg_i32 s84, 0x4000
	s_mov_b64 s[66:67], 0x168000
	s_cselect_b32 s15, s15, 0
	v_lshl_add_u64 v[82:83], v[216:217], 0, s[66:67]
	s_add_i32 s66, s84, s78
	s_mov_b32 s67, m0
	s_mov_b32 m0, s66
	s_nop 0
	global_load_lds_dwordx4 v[82:83], off
	s_mov_b32 m0, s67
	v_lshl_add_u64 v[82:83], v[218:219], 0, s[54:55]
	s_lshl_b32 s72, s15, 1
	s_add_i32 s66, s72, s79
	s_mov_b32 s67, m0
	s_mov_b32 m0, s66
	s_nop 0
	global_load_lds_dwordx4 v[82:83], off
	s_mov_b32 m0, s67
	v_max_f32_e32 v82, v66, v67
	v_max3_f32 v83, v68, v69, v51
	v_max3_f32 v82, v82, v50, v52
	v_max3_f32 v82, v82, v53, v70
	v_max3_f32 v83, v83, v72, v73
	v_max3_f32 v82, v82, v71, v54
	v_max3_f32 v83, v83, v56, v57
	v_max3_f32 v82, v82, v55, v74
	v_max3_f32 v83, v83, v76, v77
	v_max3_f32 v82, v82, v75, v58
	v_max3_f32 v83, v83, v60, v61
	v_max3_f32 v82, v82, v59, v78
	v_max3_f32 v83, v83, v80, v81
	v_max3_f32 v82, v82, v79, v62
	v_max3_f32 v83, v83, v64, v65
	v_max3_f32 v82, v82, v63, v83
	v_mov_b32_e32 v83, v82
	s_nop 1
	v_permlane32_swap_b32_e32 v82, v83
	v_max_f32_e32 v82, v82, v83
	v_cmp_lt_f32_e32 vcc, s43, v82
	s_cmp_lg_u64 vcc, 0
	v_add_f32_e32 v220, v209, v182
	s_cselect_b64 s[66:67], -1, 0
	s_cbranch_vccnz .LBB0_373

.LBB0_383:
	s_mul_i32 s66, s66, 0x48000
	s_mov_b32 s67, s7
	v_lshl_add_u64 v[82:83], v[226:227], 0, s[66:67]
	s_mov_b64 s[70:71], 0xd8400
	v_lshl_add_u64 v[82:83], v[82:83], 0, s[70:71]
	s_add_i32 s3, s15, s78
	s_ashr_i32 s67, s66, 31
	s_mov_b32 s15, m0
	s_mov_b32 m0, s3
	s_nop 0
	global_load_lds_dwordx4 v[82:83], off
	s_mov_b32 m0, s15
	v_lshl_add_u64 v[82:83], v[206:207], 0, s[66:67]
	s_lshl_b32 s3, s73, 1
	s_add_i32 s15, s3, s79
	s_mov_b32 s66, m0
	s_mov_b32 m0, s15
	s_nop 0
	global_load_lds_dwordx4 v[82:83], off
	s_mov_b32 m0, s66
	v_max_f32_e32 v82, v66, v67
	v_max3_f32 v83, v68, v69, v51
	v_max3_f32 v82, v82, v50, v52
	v_max3_f32 v82, v82, v53, v70
	v_max3_f32 v83, v83, v72, v73
	v_max3_f32 v82, v82, v71, v54
	v_max3_f32 v83, v83, v56, v57
	v_max3_f32 v82, v82, v55, v74
	v_max3_f32 v83, v83, v76, v77
	v_max3_f32 v82, v82, v75, v58
	v_max3_f32 v83, v83, v60, v61
	v_max3_f32 v82, v82, v59, v78
	v_max3_f32 v83, v83, v80, v81
	v_max3_f32 v82, v82, v79, v62
	v_max3_f32 v83, v83, v64, v65
	v_max3_f32 v82, v82, v63, v83
	v_mov_b32_e32 v83, v82
	s_nop 1
	v_permlane32_swap_b32_e32 v82, v83
	v_max_f32_e32 v82, v82, v83
	v_cmp_lt_f32_e32 vcc, s43, v82
	s_cmp_lg_u64 vcc, 0
	v_add_f32_e32 v216, v220, v170
	s_cselect_b64 s[66:67], -1, 0
	s_cbranch_vccnz .LBB0_440

.LBB0_393:
	s_add_i32 s15, s73, 0x2000
	s_cmpk_lg_i32 s73, 0x4000
	s_cselect_b32 s15, s15, 0
	s_addk_i32 s14, 0x3c0
	v_mad_u64_u32 v[82:83], s[70:71], s14, v233, v[214:215]
	s_add_i32 s14, s73, s78
	s_mov_b32 s67, m0
	s_mov_b32 m0, s14
	s_nop 0
	global_load_lds_dwordx4 v[82:83], off
	s_mov_b32 m0, s67
	s_mul_i32 s66, s66, 0x48000
	s_mov_b32 s67, s7
	v_lshl_add_u64 v[82:83], v[228:229], 0, s[66:67]
	s_lshl_b32 s14, s15, 1
	s_add_i32 s66, s14, s79
	s_mov_b32 s67, m0
	s_mov_b32 m0, s66
	s_nop 0
	global_load_lds_dwordx4 v[82:83], off
	s_mov_b32 m0, s67
	v_max_f32_e32 v82, v66, v67
	v_max3_f32 v83, v68, v69, v51
	v_max3_f32 v82, v82, v50, v52
	v_max3_f32 v82, v82, v53, v70
	v_max3_f32 v83, v83, v72, v73
	v_max3_f32 v82, v82, v71, v54
	v_max3_f32 v83, v83, v56, v57
	v_max3_f32 v82, v82, v55, v74
	v_max3_f32 v83, v83, v76, v77
	v_max3_f32 v82, v82, v75, v58
	v_max3_f32 v83, v83, v60, v61
	v_max3_f32 v82, v82, v59, v78
	v_max3_f32 v83, v83, v80, v81
	v_max3_f32 v82, v82, v79, v62
	v_max3_f32 v83, v83, v64, v65
	v_max3_f32 v82, v82, v63, v83
	v_mov_b32_e32 v83, v82
	s_nop 1
	v_permlane32_swap_b32_e32 v82, v83
	v_max_f32_e32 v82, v82, v83
	v_cmp_lt_f32_e32 vcc, s43, v82
	s_cmp_lg_u64 vcc, 0
	v_add_f32_e32 v246, v216, v198
	s_cselect_b64 s[66:67], -1, 0
	s_cbranch_vccnz .LBB0_443

.LBB0_403:
	s_add_i32 s3, s15, 0x2000
	s_cmpk_lg_i32 s15, 0x4000
	s_cselect_b32 s3, s3, 0
	s_mul_i32 s66, s66, 0x48000
	s_mov_b32 s67, s7
	v_lshl_add_u64 v[82:83], v[228:229], 0, s[66:67]
	s_lshl_b32 s15, s3, 1
	s_add_i32 s12, s15, s79
	s_mov_b32 s66, m0
	s_mov_b32 m0, s12
	s_nop 0
	global_load_lds_dwordx4 v[82:83], off
	s_mov_b32 m0, s66
	v_max_f32_e32 v82, v66, v67
	v_max3_f32 v83, v68, v69, v51
	v_max3_f32 v82, v82, v50, v52
	v_max3_f32 v82, v82, v53, v70
	v_max3_f32 v83, v83, v72, v73
	v_max3_f32 v82, v82, v71, v54
	v_max3_f32 v83, v83, v56, v57
	v_max3_f32 v82, v82, v55, v74
	v_max3_f32 v83, v83, v76, v77
	v_max3_f32 v82, v82, v75, v58
	v_max3_f32 v83, v83, v60, v61
	v_max3_f32 v82, v82, v59, v78
	v_max3_f32 v83, v83, v80, v81
	v_max3_f32 v82, v82, v79, v62
	v_max3_f32 v83, v83, v64, v65
	v_max3_f32 v82, v82, v63, v83
	v_mov_b32_e32 v83, v82
	s_nop 1
	v_permlane32_swap_b32_e32 v82, v83
	v_max_f32_e32 v82, v82, v83
	v_cmp_lt_f32_e32 vcc, s43, v82
	s_cmp_lg_u64 vcc, 0
	v_add_f32_e32 v246, v246, v198
	s_cselect_b64 s[66:67], -1, 0
	s_cbranch_vccnz .LBB0_446

.LBB0_413:
	s_add_i32 s12, s3, 0x2000
	s_cmpk_lg_i32 s3, 0x4000
	s_cselect_b32 s13, s12, 0
	s_mov_b64 s[62:63], 0x318000
	v_lshl_add_u64 v[82:83], v[230:231], 0, s[62:63]
	s_lshl_b32 s12, s13, 1
	s_add_i32 s14, s12, s79
	s_mov_b32 s62, m0
	s_mov_b32 m0, s14
	s_nop 0
	global_load_lds_dwordx4 v[82:83], off
	s_mov_b32 m0, s62
	v_max_f32_e32 v82, v66, v67
	v_max3_f32 v83, v68, v69, v51
	v_max3_f32 v82, v82, v50, v52
	v_max3_f32 v82, v82, v53, v70
	v_max3_f32 v83, v83, v72, v73
	v_max3_f32 v82, v82, v71, v54
	v_max3_f32 v83, v83, v56, v57
	v_max3_f32 v82, v82, v55, v74
	v_max3_f32 v83, v83, v76, v77
	v_max3_f32 v82, v82, v75, v58
	v_max3_f32 v83, v83, v60, v61
	v_max3_f32 v82, v82, v59, v78
	v_max3_f32 v83, v83, v80, v81
	v_max3_f32 v82, v82, v79, v62
	v_max3_f32 v83, v83, v64, v65
	v_max3_f32 v82, v82, v63, v83
	v_mov_b32_e32 v83, v82
	s_nop 1
	v_permlane32_swap_b32_e32 v82, v83
	v_max_f32_e32 v82, v82, v83
	v_cmp_lt_f32_e32 vcc, s43, v82
	s_cmp_lg_u64 vcc, 0
	v_add_f32_e32 v194, v246, v198
	s_cselect_b64 s[62:63], -1, 0
	s_cbranch_vccnz .LBB0_449

.LBB0_423:
	v_add_f32_e32 v83, v194, v66
	v_max_f32_e32 v66, v50, v51
	v_max3_f32 v67, v52, v53, v35
	v_max3_f32 v66, v66, v34, v36
	v_max3_f32 v66, v66, v37, v54
	v_max3_f32 v67, v67, v56, v57
	v_max3_f32 v66, v66, v55, v38
	v_max3_f32 v67, v67, v40, v41
	v_max3_f32 v66, v66, v39, v58
	v_max3_f32 v67, v67, v60, v61
	v_max3_f32 v66, v66, v59, v42
	v_max3_f32 v67, v67, v44, v45
	v_max3_f32 v66, v66, v43, v62
	v_max3_f32 v67, v67, v64, v65
	v_max3_f32 v66, v66, v63, v46
	v_max3_f32 v67, v67, v48, v49
	v_max3_f32 v66, v66, v47, v67
	v_mov_b32_e32 v67, v66
	s_nop 1
	v_permlane32_swap_b32_e32 v66, v67
	v_max_f32_e32 v66, v66, v67
	v_cmp_lt_f32_e32 vcc, s43, v66
	s_cmp_lg_u64 vcc, 0
	s_cselect_b64 s[60:61], -1, 0
	s_cbranch_vccnz .LBB0_452

.LBB0_488:
	v_lshl_add_u32 v0, s82, 1, v220
	ds_read_b64_tr_b16 v[192:193], v0 offset:24576
	ds_read_b64_tr_b16 v[194:195], v0 offset:25088
	s_waitcnt lgkmcnt(9)
	v_mfma_f32_32x32x16_bf16 v[112:127], v[188:191], v[148:151], v[48:63]
	v_add_f32_e32 v2, v80, v81
	v_add_f32_e32 v2, v82, v2
	v_add_f32_e32 v2, v83, v2
	v_add_f32_e32 v2, v84, v2
	v_add_f32_e32 v2, v85, v2
	v_cvt_pk_bf16_f32 v156, v80, v81
	v_cvt_pk_bf16_f32 v157, v82, v83
	ds_read_b64_tr_b16 v[188:189], v0 offset:28672
	ds_read_b64_tr_b16 v[190:191], v0 offset:29184
	s_waitcnt lgkmcnt(10)
	v_mfma_f32_32x32x16_bf16 v[96:111], v[184:187], v[148:151], v[48:63]
	v_add_f32_e32 v2, v86, v2
	v_add_f32_e32 v2, v87, v2
	v_add_f32_e32 v2, v88, v2
	v_add_f32_e32 v2, v89, v2
	v_cvt_pk_bf16_f32 v158, v84, v85
	v_cvt_pk_bf16_f32 v159, v86, v87
	ds_read_b64_tr_b16 v[184:185], v0 offset:25600
	ds_read_b64_tr_b16 v[186:187], v0 offset:26112
	s_waitcnt lgkmcnt(11)
	v_mfma_f32_32x32x16_bf16 v[112:127], v[180:183], v[140:143], v[112:127]
	v_add_f32_e32 v2, v90, v2
	v_add_f32_e32 v2, v91, v2
	v_add_f32_e32 v2, v92, v2
	v_add_f32_e32 v2, v93, v2
	v_cvt_pk_bf16_f32 v152, v88, v89
	v_cvt_pk_bf16_f32 v153, v90, v91
	ds_read_b64_tr_b16 v[84:85], v0 offset:29696
	ds_read_b64_tr_b16 v[86:87], v0 offset:30208
	s_waitcnt lgkmcnt(12)
	v_mfma_f32_32x32x16_bf16 v[96:111], v[176:179], v[140:143], v[96:111]
	v_add_f32_e32 v2, v94, v2
	v_add_f32_e32 v2, v95, v2
	v_add_f32_e32 v2, v64, v2
	v_add_f32_e32 v2, v65, v2
	v_cvt_pk_bf16_f32 v154, v92, v93
	v_cvt_pk_bf16_f32 v155, v94, v95
	ds_read_b64_tr_b16 v[80:81], v0 offset:26624
	ds_read_b64_tr_b16 v[82:83], v0 offset:27136
	s_waitcnt lgkmcnt(13)
	v_mfma_f32_32x32x16_bf16 v[112:127], v[172:175], v[132:135], v[112:127]
	v_add_f32_e32 v2, v66, v2
	v_add_f32_e32 v2, v67, v2
	v_add_f32_e32 v2, v68, v2
	v_add_f32_e32 v2, v69, v2
	v_cvt_pk_bf16_f32 v144, v64, v65
	v_cvt_pk_bf16_f32 v145, v66, v67
	ds_read_b64_tr_b16 v[10:11], v0 offset:30720
	ds_read_b64_tr_b16 v[12:13], v0 offset:31232
	s_waitcnt lgkmcnt(14)
	v_mfma_f32_32x32x16_bf16 v[96:111], v[168:171], v[132:135], v[96:111]
	v_add_f32_e32 v2, v70, v2
	v_add_f32_e32 v2, v71, v2
	v_add_f32_e32 v2, v72, v2
	v_add_f32_e32 v2, v73, v2
	v_cvt_pk_bf16_f32 v146, v68, v69
	v_cvt_pk_bf16_f32 v147, v70, v71
	ds_read_b64_tr_b16 v[6:7], v0 offset:27648
	ds_read_b64_tr_b16 v[8:9], v0 offset:28160
	s_waitcnt lgkmcnt(14)
	v_mfma_f32_32x32x16_bf16 v[112:127], v[164:167], v[128:131], v[112:127]
	v_add_f32_e32 v2, v74, v2
	v_add_f32_e32 v2, v75, v2
	v_add_f32_e32 v2, v76, v2
	v_add_f32_e32 v14, v77, v2
	v_cvt_pk_bf16_f32 v136, v72, v73
	v_cvt_pk_bf16_f32 v137, v74, v75
	ds_read_b64_tr_b16 v[2:3], v0 offset:31744
	ds_read_b64_tr_b16 v[4:5], v0 offset:32256
	v_mfma_f32_32x32x16_bf16 v[96:111], v[160:163], v[128:131], v[96:111]
	v_add_f32_e32 v0, v78, v14
	v_add_f32_e32 v0, v79, v0
	v_cvt_pk_bf16_f32 v138, v76, v77
	v_cvt_pk_bf16_f32 v139, v78, v79
	v_lshl_add_u64 v[14:15], v[200:201], 0, s[60:61]
	s_add_i32 s10, s43, s15
	s_mov_b32 s11, m0
	s_mov_b32 m0, s10
	s_nop 0
	global_load_lds_dwordx4 v[14:15], off
	s_mov_b32 m0, s11
	v_lshl_add_u64 v[14:15], v[198:199], 0, s[60:61]
	s_lshl_b32 s10, s52, 1
	s_add_i32 s10, s10, s33
	s_mov_b32 s11, m0
	s_mov_b32 m0, s10
	s_nop 0
	global_load_lds_dwordx4 v[14:15], off
	s_mov_b32 m0, s11
	v_max_f32_e32 v14, v112, v113
	v_max3_f32 v15, v114, v115, v97
	v_max3_f32 v14, v14, v96, v98
	v_max3_f32 v14, v14, v99, v116
	v_max3_f32 v15, v15, v118, v119
	v_max3_f32 v14, v14, v117, v100
	v_max3_f32 v15, v15, v102, v103
	v_max3_f32 v14, v14, v101, v120
	v_max3_f32 v15, v15, v122, v123
	v_max3_f32 v14, v14, v121, v104
	v_max3_f32 v15, v15, v106, v107
	v_max3_f32 v14, v14, v105, v124
	v_max3_f32 v15, v15, v126, v127
	v_max3_f32 v64, v14, v125, v108
	v_max3_f32 v15, v15, v110, v111
	v_add_f32_e32 v14, v225, v0
	v_max3_f32 v0, v64, v109, v15
	v_mov_b32_e32 v15, v0
	s_nop 1
	v_permlane32_swap_b32_e32 v0, v15
	v_max_f32_e32 v0, v0, v15
	v_cmp_lt_f32_e32 vcc, s13, v0
	s_cmp_lg_u64 vcc, 0
	s_cselect_b64 s[10:11], -1, 0
	s_cbranch_vccnz .LBB0_496

.LBB0_491:
	s_add_i32 s10, s52, 0x2000
	s_cmpk_lg_i32 s52, 0x4000
	s_cselect_b32 s80, s10, 0
	v_lshl_add_u32 v4, s43, 1, v220
	ds_read_b64_tr_b16 v[168:169], v4 offset:24576
	ds_read_b64_tr_b16 v[170:171], v4 offset:25088
	s_waitcnt lgkmcnt(9)
	v_mfma_f32_32x32x16_bf16 v[80:95], v[64:67], v[148:151], v[48:63]
	v_add_f32_e32 v2, v112, v113
	v_add_f32_e32 v2, v114, v2
	v_add_f32_e32 v2, v115, v2
	v_add_f32_e32 v2, v116, v2
	v_add_f32_e32 v2, v117, v2
	v_cvt_pk_bf16_f32 v156, v112, v113
	v_cvt_pk_bf16_f32 v157, v114, v115
	ds_read_b64_tr_b16 v[164:165], v4 offset:28672
	ds_read_b64_tr_b16 v[166:167], v4 offset:29184
	s_waitcnt lgkmcnt(10)
	v_mfma_f32_32x32x16_bf16 v[64:79], v[160:163], v[148:151], v[48:63]
	v_add_f32_e32 v2, v118, v2
	v_add_f32_e32 v2, v119, v2
	v_add_f32_e32 v2, v120, v2
	v_add_f32_e32 v2, v121, v2
	v_cvt_pk_bf16_f32 v158, v116, v117
	v_cvt_pk_bf16_f32 v159, v118, v119
	ds_read_b64_tr_b16 v[160:161], v4 offset:25600
	ds_read_b64_tr_b16 v[162:163], v4 offset:26112
	s_waitcnt lgkmcnt(11)
	v_mfma_f32_32x32x16_bf16 v[80:95], v[192:195], v[140:143], v[80:95]
	v_add_f32_e32 v2, v122, v2
	v_add_f32_e32 v2, v123, v2
	v_add_f32_e32 v2, v124, v2
	v_add_f32_e32 v2, v125, v2
	v_cvt_pk_bf16_f32 v152, v120, v121
	v_cvt_pk_bf16_f32 v153, v122, v123
	ds_read_b64_tr_b16 v[116:117], v4 offset:29696
	ds_read_b64_tr_b16 v[118:119], v4 offset:30208
	s_waitcnt lgkmcnt(12)
	v_mfma_f32_32x32x16_bf16 v[64:79], v[184:187], v[140:143], v[64:79]
	v_add_f32_e32 v2, v126, v2
	v_add_f32_e32 v2, v127, v2
	v_add_f32_e32 v2, v96, v2
	v_add_f32_e32 v2, v97, v2
	v_cvt_pk_bf16_f32 v154, v124, v125
	v_cvt_pk_bf16_f32 v155, v126, v127
	ds_read_b64_tr_b16 v[112:113], v4 offset:26624
	ds_read_b64_tr_b16 v[114:115], v4 offset:27136
	s_waitcnt lgkmcnt(13)
	v_mfma_f32_32x32x16_bf16 v[80:95], v[188:191], v[132:135], v[80:95]
	v_add_f32_e32 v2, v98, v2
	v_add_f32_e32 v2, v99, v2
	v_add_f32_e32 v2, v100, v2
	v_add_f32_e32 v2, v101, v2
	v_cvt_pk_bf16_f32 v144, v96, v97
	v_cvt_pk_bf16_f32 v145, v98, v99
	ds_read_b64_tr_b16 v[10:11], v4 offset:30720
	ds_read_b64_tr_b16 v[12:13], v4 offset:31232
	s_waitcnt lgkmcnt(14)
	v_mfma_f32_32x32x16_bf16 v[64:79], v[176:179], v[132:135], v[64:79]
	v_add_f32_e32 v2, v102, v2
	v_add_f32_e32 v2, v103, v2
	v_add_f32_e32 v2, v104, v2
	v_add_f32_e32 v2, v105, v2
	v_cvt_pk_bf16_f32 v146, v100, v101
	v_cvt_pk_bf16_f32 v147, v102, v103
	ds_read_b64_tr_b16 v[6:7], v4 offset:27648
	ds_read_b64_tr_b16 v[8:9], v4 offset:28160
	s_waitcnt lgkmcnt(14)
	v_mfma_f32_32x32x16_bf16 v[80:95], v[180:183], v[128:131], v[80:95]
	v_add_f32_e32 v2, v106, v2
	v_add_f32_e32 v2, v107, v2
	v_add_f32_e32 v2, v108, v2
	v_add_f32_e32 v15, v109, v2
	v_cvt_pk_bf16_f32 v136, v104, v105
	v_cvt_pk_bf16_f32 v137, v106, v107
	ds_read_b64_tr_b16 v[2:3], v4 offset:31744
	ds_read_b64_tr_b16 v[4:5], v4 offset:32256
	v_mfma_f32_32x32x16_bf16 v[64:79], v[172:175], v[128:131], v[64:79]
	v_add_f32_e32 v15, v110, v15
	v_add_f32_e32 v15, v111, v15
	v_cvt_pk_bf16_f32 v138, v108, v109
	v_cvt_pk_bf16_f32 v139, v110, v111
	v_max_f32_e32 v96, v81, v81
	v_max_f32_e32 v97, v80, v80
	v_max_f32_e32 v96, v97, v96
	s_nop 3
	s_nop 0
	v_max3_f32 v97, v82, v83, v65
	v_max3_f32 v96, v96, v64, v66
	v_max3_f32 v96, v96, v67, v84
	v_max3_f32 v97, v97, v86, v87
	v_max3_f32 v96, v96, v85, v68
	v_max3_f32 v97, v97, v70, v71
	v_max3_f32 v96, v96, v69, v88
	v_max3_f32 v97, v97, v90, v91
	v_max3_f32 v96, v96, v89, v72
	v_max3_f32 v97, v97, v74, v75
	v_max3_f32 v96, v96, v73, v92
	v_max3_f32 v97, v97, v94, v95
	v_max3_f32 v96, v96, v93, v76
	v_max3_f32 v97, v97, v78, v79
	v_add_f32_e32 v225, v14, v15
	v_max3_f32 v14, v96, v77, v97
	v_mov_b32_e32 v15, v14
	s_nop 1
	v_permlane32_swap_b32_e32 v14, v15
	s_add_i32 s10, s52, s15
	s_mov_b32 s11, m0
	s_mov_b32 m0, s10
	s_nop 0
	global_load_lds_dwordx4 v[200:201], off
	s_mov_b32 m0, s11
	s_lshl_b32 s10, s80, 1
	v_max_f32_e32 v14, v14, v15
	s_add_i32 s10, s10, s33
	s_mov_b32 s11, m0
	s_mov_b32 m0, s10
	s_nop 0
	global_load_lds_dwordx4 v[198:199], off
	s_mov_b32 m0, s11
	v_cmp_lt_f32_e32 vcc, s13, v14
	s_cmp_lg_u64 vcc, 0
	s_cselect_b64 s[10:11], -1, 0
	s_cbranch_vccnz .LBB0_499

.LBB0_508:
	v_lshl_add_u32 v0, s82, 1, v220
	ds_read_b64_tr_b16 v[196:197], v0 offset:24576
	ds_read_b64_tr_b16 v[198:199], v0 offset:25088
	s_waitcnt lgkmcnt(9)
	v_mfma_f32_32x32x16_bf16 v[112:127], v[188:191], v[148:151], v[48:63]
	v_add_f32_e32 v2, v80, v81
	v_add_f32_e32 v2, v82, v2
	v_add_f32_e32 v2, v83, v2
	v_add_f32_e32 v2, v84, v2
	v_add_f32_e32 v2, v85, v2
	v_cvt_pk_bf16_f32 v156, v80, v81
	v_cvt_pk_bf16_f32 v157, v82, v83
	ds_read_b64_tr_b16 v[188:189], v0 offset:28672
	ds_read_b64_tr_b16 v[190:191], v0 offset:29184
	s_waitcnt lgkmcnt(10)
	v_mfma_f32_32x32x16_bf16 v[96:111], v[184:187], v[148:151], v[48:63]
	v_add_f32_e32 v2, v86, v2
	v_add_f32_e32 v2, v87, v2
	v_add_f32_e32 v2, v88, v2
	v_add_f32_e32 v2, v89, v2
	v_cvt_pk_bf16_f32 v158, v84, v85
	v_cvt_pk_bf16_f32 v159, v86, v87
	ds_read_b64_tr_b16 v[192:193], v0 offset:25600
	ds_read_b64_tr_b16 v[194:195], v0 offset:26112
	s_waitcnt lgkmcnt(11)
	v_mfma_f32_32x32x16_bf16 v[112:127], v[180:183], v[140:143], v[112:127]
	v_add_f32_e32 v2, v90, v2
	v_add_f32_e32 v2, v91, v2
	v_add_f32_e32 v2, v92, v2
	v_add_f32_e32 v2, v93, v2
	v_cvt_pk_bf16_f32 v152, v88, v89
	v_cvt_pk_bf16_f32 v153, v90, v91
	ds_read_b64_tr_b16 v[84:85], v0 offset:29696
	ds_read_b64_tr_b16 v[86:87], v0 offset:30208
	s_waitcnt lgkmcnt(12)
	v_mfma_f32_32x32x16_bf16 v[96:111], v[176:179], v[140:143], v[96:111]
	v_add_f32_e32 v2, v94, v2
	v_add_f32_e32 v2, v95, v2
	v_add_f32_e32 v2, v64, v2
	v_add_f32_e32 v2, v65, v2
	v_cvt_pk_bf16_f32 v154, v92, v93
	v_cvt_pk_bf16_f32 v155, v94, v95
	ds_read_b64_tr_b16 v[80:81], v0 offset:26624
	ds_read_b64_tr_b16 v[82:83], v0 offset:27136
	s_waitcnt lgkmcnt(13)
	v_mfma_f32_32x32x16_bf16 v[112:127], v[172:175], v[132:135], v[112:127]
	v_add_f32_e32 v2, v66, v2
	v_add_f32_e32 v2, v67, v2
	v_add_f32_e32 v2, v68, v2
	v_add_f32_e32 v2, v69, v2
	v_cvt_pk_bf16_f32 v144, v64, v65
	v_cvt_pk_bf16_f32 v145, v66, v67
	ds_read_b64_tr_b16 v[10:11], v0 offset:30720
	ds_read_b64_tr_b16 v[12:13], v0 offset:31232
	s_waitcnt lgkmcnt(14)
	v_mfma_f32_32x32x16_bf16 v[96:111], v[168:171], v[132:135], v[96:111]
	v_add_f32_e32 v2, v70, v2
	v_add_f32_e32 v2, v71, v2
	v_add_f32_e32 v2, v72, v2
	v_add_f32_e32 v2, v73, v2
	v_cvt_pk_bf16_f32 v146, v68, v69
	v_cvt_pk_bf16_f32 v147, v70, v71
	ds_read_b64_tr_b16 v[6:7], v0 offset:27648
	ds_read_b64_tr_b16 v[8:9], v0 offset:28160
	s_waitcnt lgkmcnt(14)
	v_mfma_f32_32x32x16_bf16 v[112:127], v[164:167], v[128:131], v[112:127]
	v_add_f32_e32 v2, v74, v2
	v_add_f32_e32 v2, v75, v2
	v_add_f32_e32 v2, v76, v2
	v_add_f32_e32 v64, v77, v2
	v_cvt_pk_bf16_f32 v136, v72, v73
	v_cvt_pk_bf16_f32 v137, v74, v75
	ds_read_b64_tr_b16 v[2:3], v0 offset:31744
	ds_read_b64_tr_b16 v[4:5], v0 offset:32256
	v_mfma_f32_32x32x16_bf16 v[96:111], v[160:163], v[128:131], v[96:111]
	v_add_f32_e32 v0, v78, v64
	v_add_f32_e32 v0, v79, v0
	v_cvt_pk_bf16_f32 v138, v76, v77
	v_cvt_pk_bf16_f32 v139, v78, v79
	s_add_i32 s10, s86, 3
	s_cmp_ge_u32 s10, s39
	s_cselect_b64 s[78:79], -1, 0
	s_and_b64 vcc, exec, s[78:79]
	s_cbranch_vccnz .LBB0_510
	v_lshl_add_u64 v[64:65], v[208:209], 0, s[60:61]
	s_add_i32 s10, s43, s15
	s_mov_b32 s11, m0
	s_mov_b32 m0, s10
	s_nop 0
	global_load_lds_dwordx4 v[64:65], off
	s_mov_b32 m0, s11
.LBB0_510:
	v_add_f32_e32 v225, v225, v0
	v_max_f32_e32 v0, v112, v113
	v_max3_f32 v64, v114, v115, v97
	v_max3_f32 v0, v0, v96, v98
	v_max3_f32 v0, v0, v99, v116
	v_max3_f32 v64, v64, v118, v119
	v_max3_f32 v0, v0, v117, v100
	v_max3_f32 v64, v64, v102, v103
	v_max3_f32 v0, v0, v101, v120
	v_max3_f32 v64, v64, v122, v123
	v_max3_f32 v0, v0, v121, v104
	v_max3_f32 v64, v64, v106, v107
	v_max3_f32 v0, v0, v105, v124
	v_max3_f32 v64, v64, v126, v127
	v_max3_f32 v0, v0, v125, v108
	v_max3_f32 v64, v64, v110, v111
	v_max3_f32 v0, v0, v109, v64
	v_mov_b32_e32 v64, v0
	s_nop 1
	v_permlane32_swap_b32_e32 v0, v64
	s_lshl_b32 s89, s52, 1
	v_max_f32_e32 v0, v0, v64
	s_add_i32 s10, s89, s33
	s_mov_b32 s11, m0
	s_mov_b32 m0, s10
	s_nop 0
	global_load_lds_dwordx4 v[14:15], off
	s_mov_b32 m0, s11
	v_cmp_lt_f32_e32 vcc, s13, v0
	s_cmp_lg_u64 vcc, 0
	s_cselect_b64 s[10:11], -1, 0
	s_cbranch_vccnz .LBB0_546

.LBB0_519:
	v_lshl_add_u32 v4, s43, 1, v220
	ds_read_b64_tr_b16 v[200:201], v4 offset:24576
	ds_read_b64_tr_b16 v[202:203], v4 offset:25088
	s_waitcnt lgkmcnt(9)
	v_mfma_f32_32x32x16_bf16 v[80:95], v[188:191], v[148:151], v[48:63]
	v_add_f32_e32 v2, v112, v113
	v_add_f32_e32 v2, v114, v2
	v_add_f32_e32 v2, v115, v2
	v_add_f32_e32 v2, v116, v2
	v_add_f32_e32 v2, v117, v2
	v_cvt_pk_bf16_f32 v156, v112, v113
	v_cvt_pk_bf16_f32 v157, v114, v115
	ds_read_b64_tr_b16 v[196:197], v4 offset:28672
	ds_read_b64_tr_b16 v[198:199], v4 offset:29184
	s_waitcnt lgkmcnt(10)
	v_mfma_f32_32x32x16_bf16 v[64:79], v[184:187], v[148:151], v[48:63]
	v_add_f32_e32 v2, v118, v2
	v_add_f32_e32 v2, v119, v2
	v_add_f32_e32 v2, v120, v2
	v_add_f32_e32 v2, v121, v2
	v_cvt_pk_bf16_f32 v158, v116, v117
	v_cvt_pk_bf16_f32 v159, v118, v119
	ds_read_b64_tr_b16 v[192:193], v4 offset:25600
	ds_read_b64_tr_b16 v[194:195], v4 offset:26112
	s_waitcnt lgkmcnt(11)
	v_mfma_f32_32x32x16_bf16 v[80:95], v[180:183], v[140:143], v[80:95]
	v_add_f32_e32 v2, v122, v2
	v_add_f32_e32 v2, v123, v2
	v_add_f32_e32 v2, v124, v2
	v_add_f32_e32 v2, v125, v2
	v_cvt_pk_bf16_f32 v152, v120, v121
	v_cvt_pk_bf16_f32 v153, v122, v123
	ds_read_b64_tr_b16 v[116:117], v4 offset:29696
	ds_read_b64_tr_b16 v[118:119], v4 offset:30208
	s_waitcnt lgkmcnt(12)
	v_mfma_f32_32x32x16_bf16 v[64:79], v[176:179], v[140:143], v[64:79]
	v_add_f32_e32 v2, v126, v2
	v_add_f32_e32 v2, v127, v2
	v_add_f32_e32 v2, v96, v2
	v_add_f32_e32 v2, v97, v2
	v_cvt_pk_bf16_f32 v154, v124, v125
	v_cvt_pk_bf16_f32 v155, v126, v127
	ds_read_b64_tr_b16 v[112:113], v4 offset:26624
	ds_read_b64_tr_b16 v[114:115], v4 offset:27136
	s_waitcnt lgkmcnt(13)
	v_mfma_f32_32x32x16_bf16 v[80:95], v[172:175], v[132:135], v[80:95]
	v_add_f32_e32 v2, v98, v2
	v_add_f32_e32 v2, v99, v2
	v_add_f32_e32 v2, v100, v2
	v_add_f32_e32 v2, v101, v2
	v_cvt_pk_bf16_f32 v144, v96, v97
	v_cvt_pk_bf16_f32 v145, v98, v99
	ds_read_b64_tr_b16 v[10:11], v4 offset:30720
	ds_read_b64_tr_b16 v[12:13], v4 offset:31232
	s_waitcnt lgkmcnt(14)
	v_mfma_f32_32x32x16_bf16 v[64:79], v[168:171], v[132:135], v[64:79]
	v_add_f32_e32 v2, v102, v2
	v_add_f32_e32 v2, v103, v2
	v_add_f32_e32 v2, v104, v2
	v_add_f32_e32 v2, v105, v2
	v_cvt_pk_bf16_f32 v146, v100, v101
	v_cvt_pk_bf16_f32 v147, v102, v103
	ds_read_b64_tr_b16 v[6:7], v4 offset:27648
	ds_read_b64_tr_b16 v[8:9], v4 offset:28160
	s_waitcnt lgkmcnt(14)
	v_mfma_f32_32x32x16_bf16 v[80:95], v[164:167], v[128:131], v[80:95]
	v_add_f32_e32 v2, v106, v2
	v_add_f32_e32 v2, v107, v2
	v_add_f32_e32 v2, v108, v2
	v_add_f32_e32 v96, v109, v2
	v_cvt_pk_bf16_f32 v136, v104, v105
	v_cvt_pk_bf16_f32 v137, v106, v107
	ds_read_b64_tr_b16 v[2:3], v4 offset:31744
	ds_read_b64_tr_b16 v[4:5], v4 offset:32256
	v_mfma_f32_32x32x16_bf16 v[64:79], v[160:163], v[128:131], v[64:79]
	v_add_f32_e32 v96, v110, v96
	v_add_f32_e32 v96, v111, v96
	v_cvt_pk_bf16_f32 v138, v108, v109
	v_cvt_pk_bf16_f32 v139, v110, v111
	s_cmp_ge_u32 s86, s88
	s_cselect_b64 s[80:81], -1, 0
	s_and_b64 vcc, exec, s[80:81]
	s_cbranch_vccnz .LBB0_521
	s_add_i32 s10, s52, s15
	s_mov_b32 s11, m0
	s_mov_b32 m0, s10
	s_nop 0
	global_load_lds_dwordx4 v[208:209], off
	s_mov_b32 m0, s11

.LBB0_523:
	v_add_f32_e32 v225, v225, v96
	v_max_f32_e32 v96, v80, v81
	v_max3_f32 v97, v82, v83, v65
	v_max3_f32 v96, v96, v64, v66
	v_max3_f32 v96, v96, v67, v84
	v_max3_f32 v97, v97, v86, v87
	v_max3_f32 v96, v96, v85, v68
	v_max3_f32 v97, v97, v70, v71
	v_max3_f32 v96, v96, v69, v88
	v_max3_f32 v97, v97, v90, v91
	v_max3_f32 v96, v96, v89, v72
	v_max3_f32 v97, v97, v74, v75
	v_max3_f32 v96, v96, v73, v92
	v_max3_f32 v97, v97, v94, v95
	v_max3_f32 v96, v96, v93, v76
	v_max3_f32 v97, v97, v78, v79
	v_max3_f32 v96, v96, v77, v97
	v_mov_b32_e32 v97, v96
	s_nop 1
	v_permlane32_swap_b32_e32 v96, v97
	v_max_f32_e32 v96, v96, v97
	v_cmp_lt_f32_e32 vcc, s13, v96
	s_cmp_lg_u64 vcc, 0
	s_cselect_b64 s[82:83], -1, 0
	s_cbranch_vccnz .LBB0_549

.LBB0_554:
	v_add_u32_e32 v0, s89, v220
	ds_read_b64_tr_b16 v[120:121], v0 offset:24576
	ds_read_b64_tr_b16 v[122:123], v0 offset:25088
	s_waitcnt lgkmcnt(9)
	v_mfma_f32_32x32x16_bf16 v[96:111], v[188:191], v[148:151], v[48:63]
	v_add_f32_e32 v2, v80, v81
	v_add_f32_e32 v2, v82, v2
	v_add_f32_e32 v2, v83, v2
	v_add_f32_e32 v2, v84, v2
	v_add_f32_e32 v2, v85, v2
	v_cvt_pk_bf16_f32 v156, v80, v81
	v_cvt_pk_bf16_f32 v157, v82, v83
	ds_read_b64_tr_b16 v[116:117], v0 offset:28672
	ds_read_b64_tr_b16 v[118:119], v0 offset:29184
	s_waitcnt lgkmcnt(10)
	v_mfma_f32_32x32x16_bf16 v[48:63], v[184:187], v[148:151], v[48:63]
	v_add_f32_e32 v2, v86, v2
	v_add_f32_e32 v2, v87, v2
	v_add_f32_e32 v2, v88, v2
	v_add_f32_e32 v2, v89, v2
	v_cvt_pk_bf16_f32 v158, v84, v85
	v_cvt_pk_bf16_f32 v159, v86, v87
	ds_read_b64_tr_b16 v[112:113], v0 offset:25600
	ds_read_b64_tr_b16 v[114:115], v0 offset:26112
	s_waitcnt lgkmcnt(11)
	v_mfma_f32_32x32x16_bf16 v[96:111], v[180:183], v[140:143], v[96:111]
	v_add_f32_e32 v2, v90, v2
	v_add_f32_e32 v2, v91, v2
	v_add_f32_e32 v2, v92, v2
	v_add_f32_e32 v2, v93, v2
	v_cvt_pk_bf16_f32 v152, v88, v89
	v_cvt_pk_bf16_f32 v153, v90, v91
	ds_read_b64_tr_b16 v[84:85], v0 offset:29696
	ds_read_b64_tr_b16 v[86:87], v0 offset:30208
	s_waitcnt lgkmcnt(12)
	v_mfma_f32_32x32x16_bf16 v[48:63], v[176:179], v[140:143], v[48:63]
	v_add_f32_e32 v2, v94, v2
	v_add_f32_e32 v2, v95, v2
	v_add_f32_e32 v2, v64, v2
	v_add_f32_e32 v2, v65, v2
	v_cvt_pk_bf16_f32 v154, v92, v93
	v_cvt_pk_bf16_f32 v155, v94, v95
	ds_read_b64_tr_b16 v[80:81], v0 offset:26624
	ds_read_b64_tr_b16 v[82:83], v0 offset:27136
	s_waitcnt lgkmcnt(13)
	v_mfma_f32_32x32x16_bf16 v[96:111], v[172:175], v[132:135], v[96:111]
	v_add_f32_e32 v2, v66, v2
	v_add_f32_e32 v2, v67, v2
	v_add_f32_e32 v2, v68, v2
	v_add_f32_e32 v2, v69, v2
	v_cvt_pk_bf16_f32 v144, v64, v65
	v_cvt_pk_bf16_f32 v145, v66, v67
	ds_read_b64_tr_b16 v[10:11], v0 offset:30720
	ds_read_b64_tr_b16 v[12:13], v0 offset:31232
	s_waitcnt lgkmcnt(14)
	v_mfma_f32_32x32x16_bf16 v[48:63], v[168:171], v[132:135], v[48:63]
	v_add_f32_e32 v2, v70, v2
	v_add_f32_e32 v2, v71, v2
	v_add_f32_e32 v2, v72, v2
	v_add_f32_e32 v2, v73, v2
	v_cvt_pk_bf16_f32 v146, v68, v69
	v_cvt_pk_bf16_f32 v147, v70, v71
	ds_read_b64_tr_b16 v[6:7], v0 offset:27648
	ds_read_b64_tr_b16 v[8:9], v0 offset:28160
	s_waitcnt lgkmcnt(14)
	v_mfma_f32_32x32x16_bf16 v[96:111], v[164:167], v[128:131], v[96:111]
	v_add_f32_e32 v2, v74, v2
	v_add_f32_e32 v2, v75, v2
	v_add_f32_e32 v2, v76, v2
	v_add_f32_e32 v14, v77, v2
	v_cvt_pk_bf16_f32 v136, v72, v73
	v_cvt_pk_bf16_f32 v137, v74, v75
	ds_read_b64_tr_b16 v[2:3], v0 offset:31744
	ds_read_b64_tr_b16 v[4:5], v0 offset:32256
	v_mfma_f32_32x32x16_bf16 v[48:63], v[160:163], v[128:131], v[48:63]
	v_add_f32_e32 v0, v78, v14
	v_add_f32_e32 v0, v79, v0
	v_cvt_pk_bf16_f32 v138, v76, v77
	v_cvt_pk_bf16_f32 v139, v78, v79
	s_and_b64 vcc, exec, s[6:7]
	s_cbranch_vccnz .LBB0_556
	s_sub_u32 s6, s74, s70
	s_subb_u32 s7, s75, s71
	s_sub_u32 s10, s76, s72
	s_subb_u32 s11, s77, s73
	v_lshl_add_u64 v[14:15], v[204:205], 0, s[6:7]
	s_add_i32 s6, s82, s15
	s_mov_b32 s7, m0
	s_mov_b32 m0, s6
	s_nop 0
	global_load_lds_dwordx4 v[14:15], off
	s_mov_b32 m0, s7
	s_lshl_b32 s6, s82, 1
	v_lshl_add_u64 v[64:65], v[206:207], 0, s[10:11]
	s_add_i32 s6, s6, s33
	s_mov_b32 s7, m0
	s_mov_b32 m0, s6
	s_nop 0
	global_load_lds_dwordx4 v[64:65], off
	s_mov_b32 m0, s7
	v_lshl_add_u64 v[64:65], v[14:15], 0, s[54:55]
	s_add_i32 s6, s8, s15
	s_mov_b32 s7, m0
	s_mov_b32 m0, s6
	s_nop 0
	global_load_lds_dwordx4 v[64:65], off
	s_mov_b32 m0, s7
	v_lshl_add_u64 v[14:15], v[14:15], 0, s[56:57]
	s_add_i32 s6, s43, s15
	s_mov_b32 s7, m0
	s_mov_b32 m0, s6
	s_nop 0
	global_load_lds_dwordx4 v[14:15], off
	s_mov_b32 m0, s7
.LBB0_556:
	v_max_f32_e32 v14, v97, v97
	v_max_f32_e32 v15, v96, v96
	v_max_f32_e32 v14, v15, v14
	s_nop 1
	v_max3_f32 v15, v98, v99, v49
	v_max3_f32 v14, v14, v48, v50
	v_max3_f32 v14, v14, v51, v100
	v_max3_f32 v15, v15, v102, v103
	v_max3_f32 v14, v14, v101, v52
	v_max3_f32 v15, v15, v54, v55
	v_max3_f32 v14, v14, v53, v104
	v_max3_f32 v15, v15, v106, v107
	v_max3_f32 v14, v14, v105, v56
	v_max3_f32 v15, v15, v58, v59
	v_max3_f32 v14, v14, v57, v108
	v_max3_f32 v15, v15, v110, v111
	v_max3_f32 v14, v14, v109, v60
	v_max3_f32 v15, v15, v62, v63
	v_max3_f32 v14, v14, v61, v15
	v_mov_b32_e32 v15, v14
	s_nop 1
	v_permlane32_swap_b32_e32 v14, v15
	v_max_f32_e32 v14, v14, v15
	v_cmp_lt_f32_e32 vcc, s13, v14
	s_cmp_lg_u64 vcc, 0
	v_add_f32_e32 v0, v225, v0
	s_cselect_b64 s[6:7], -1, 0
	s_cbranch_vccnz .LBB0_561

.LBB0_1126:
	s_lshl_b32 s4, s9, 1
	v_add_u32_e32 v216, s4, v247
	ds_read_b64_tr_b16 v[226:227], v216 offset:24576
	ds_read_b64_tr_b16 v[228:229], v216 offset:25088
	s_waitcnt lgkmcnt(9)
	v_mfma_f32_32x32x16_bf16 v[130:145], v[206:209], v[174:177], v[66:81]
	v_add_f32_e32 v1, v98, v99
	v_add_f32_e32 v1, v100, v1
	v_add_f32_e32 v1, v101, v1
	v_add_f32_e32 v1, v102, v1
	v_add_f32_e32 v1, v103, v1
	v_cvt_pk_bf16_f32 v158, v98, v99
	v_cvt_pk_bf16_f32 v159, v100, v101
	ds_read_b64_tr_b16 v[250:251], v216 offset:28672
	ds_read_b64_tr_b16 v[252:253], v216 offset:29184
	s_waitcnt lgkmcnt(10)
	v_mfma_f32_32x32x16_bf16 v[114:129], v[198:201], v[174:177], v[66:81]
	v_add_f32_e32 v1, v104, v1
	v_add_f32_e32 v1, v105, v1
	v_add_f32_e32 v1, v106, v1
	v_add_f32_e32 v1, v107, v1
	v_cvt_pk_bf16_f32 v160, v102, v103
	v_cvt_pk_bf16_f32 v161, v104, v105
	ds_read_b64_tr_b16 v[198:199], v216 offset:25600
	ds_read_b64_tr_b16 v[200:201], v216 offset:26112
	s_waitcnt lgkmcnt(11)
	v_mfma_f32_32x32x16_bf16 v[130:145], v[202:205], v[170:173], v[130:145]
	v_add_f32_e32 v1, v108, v1
	v_add_f32_e32 v1, v109, v1
	v_add_f32_e32 v1, v110, v1
	v_add_f32_e32 v1, v111, v1
	v_cvt_pk_bf16_f32 v154, v106, v107
	v_cvt_pk_bf16_f32 v155, v108, v109
	ds_read_b64_tr_b16 v[106:107], v216 offset:29696
	ds_read_b64_tr_b16 v[108:109], v216 offset:30208
	s_waitcnt lgkmcnt(12)
	v_mfma_f32_32x32x16_bf16 v[114:129], v[194:197], v[170:173], v[114:129]
	v_add_f32_e32 v1, v112, v1
	v_add_f32_e32 v1, v113, v1
	v_add_f32_e32 v1, v82, v1
	v_add_f32_e32 v1, v83, v1
	v_cvt_pk_bf16_f32 v156, v110, v111
	v_cvt_pk_bf16_f32 v157, v112, v113
	ds_read_b64_tr_b16 v[102:103], v216 offset:26624
	ds_read_b64_tr_b16 v[104:105], v216 offset:27136
	s_waitcnt lgkmcnt(13)
	v_mfma_f32_32x32x16_bf16 v[130:145], v[190:193], v[166:169], v[130:145]
	v_add_f32_e32 v1, v84, v1
	v_add_f32_e32 v1, v85, v1
	v_add_f32_e32 v1, v86, v1
	v_add_f32_e32 v1, v87, v1
	v_cvt_pk_bf16_f32 v150, v82, v83
	v_cvt_pk_bf16_f32 v151, v84, v85
	ds_read_b64_tr_b16 v[98:99], v216 offset:30720
	ds_read_b64_tr_b16 v[100:101], v216 offset:31232
	s_waitcnt lgkmcnt(14)
	v_mfma_f32_32x32x16_bf16 v[114:129], v[186:189], v[166:169], v[114:129]
	v_add_f32_e32 v1, v88, v1
	v_add_f32_e32 v1, v89, v1
	v_add_f32_e32 v1, v90, v1
	v_add_f32_e32 v1, v91, v1
	v_cvt_pk_bf16_f32 v152, v86, v87
	v_cvt_pk_bf16_f32 v153, v88, v89
	ds_read_b64_tr_b16 v[86:87], v216 offset:27648
	ds_read_b64_tr_b16 v[88:89], v216 offset:28160
	s_waitcnt lgkmcnt(14)
	v_mfma_f32_32x32x16_bf16 v[130:145], v[182:185], v[162:165], v[130:145]
	v_add_f32_e32 v1, v92, v1
	v_add_f32_e32 v1, v93, v1
	v_add_f32_e32 v1, v94, v1
	v_add_f32_e32 v1, v95, v1
	v_cvt_pk_bf16_f32 v146, v90, v91
	v_cvt_pk_bf16_f32 v147, v92, v93
	ds_read_b64_tr_b16 v[90:91], v216 offset:31744
	ds_read_b64_tr_b16 v[92:93], v216 offset:32256
	v_mfma_f32_32x32x16_bf16 v[114:129], v[178:181], v[162:165], v[114:129]
	v_add_f32_e32 v1, v96, v1
	v_add_f32_e32 v1, v97, v1
	v_cvt_pk_bf16_f32 v148, v94, v95
	v_cvt_pk_bf16_f32 v149, v96, v97
	s_add_i32 s4, s15, s55
	v_lshl_add_u64 v[82:83], v[212:213], 0, s[62:63]
	s_mov_b32 s8, m0
	s_mov_b32 m0, s4
	s_nop 0
	global_load_lds_dwordx4 v[82:83], off
	s_mov_b32 m0, s8
	s_lshl_b32 s4, s84, 1
	s_waitcnt lgkmcnt(14)
	v_mfma_f32_32x32x16_bf16 v[50:65], v[158:161], v[226:229], v[50:65]
	v_lshl_add_u64 v[82:83], v[214:215], 0, s[58:59]
	s_add_i32 s4, s4, s1
	s_mov_b32 s8, m0
	s_mov_b32 m0, s4
	s_nop 0
	global_load_lds_dwordx4 v[82:83], off
	s_mov_b32 m0, s8
	v_lshl_add_u64 v[82:83], v[214:215], 0, s[64:65]
	s_addk_i32 s4, 0x2000
	s_mov_b32 s8, m0
	s_mov_b32 m0, s4
	s_nop 0
	global_load_lds_dwordx4 v[82:83], off
	s_mov_b32 m0, s8
	ds_read_b64_tr_b16 v[206:207], v216 offset:32768
	ds_read_b64_tr_b16 v[208:209], v216 offset:33280
	s_waitcnt lgkmcnt(14)
	v_mfma_f32_32x32x16_bf16 v[34:49], v[158:161], v[250:253], v[34:49]
	ds_read_b64_tr_b16 v[110:111], v216 offset:36864
	ds_read_b64_tr_b16 v[112:113], v216 offset:37376
	s_waitcnt lgkmcnt(14)
	v_mfma_f32_32x32x16_bf16 v[50:65], v[154:157], v[198:201], v[50:65]
	ds_read_b64_tr_b16 v[94:95], v216 offset:33792
	ds_read_b64_tr_b16 v[96:97], v216 offset:34304
	v_max_f32_e32 v82, v130, v131
	v_max3_f32 v83, v132, v133, v115
	v_max3_f32 v82, v82, v114, v116
	v_max3_f32 v82, v82, v117, v134
	v_max3_f32 v83, v83, v136, v137
	v_max3_f32 v82, v82, v135, v118
	v_max3_f32 v83, v83, v120, v121
	v_max3_f32 v82, v82, v119, v138
	v_max3_f32 v83, v83, v140, v141
	v_max3_f32 v82, v82, v139, v122
	v_max3_f32 v83, v83, v124, v125
	v_max3_f32 v82, v82, v123, v142
	v_max3_f32 v83, v83, v144, v145
	v_max3_f32 v82, v82, v143, v126
	v_max3_f32 v83, v83, v128, v129
	v_max3_f32 v82, v82, v127, v83
	v_mov_b32_e32 v83, v82
	s_nop 1
	v_permlane32_swap_b32_e32 v82, v83
	v_max_f32_e32 v82, v82, v83
	v_cmp_lt_f32_e32 vcc, s13, v82
	s_cmp_lg_u64 vcc, 0
	v_add_f32_e32 v1, v249, v1
	s_cselect_b64 s[86:87], -1, 0
	s_cbranch_vccnz .LBB0_1134
.LBB0_1127:
	v_add_u32_e32 v178, s84, v248
	ds_read_b128 v[82:85], v178
	ds_read_b128 v[198:201], v178 offset:512
	s_waitcnt lgkmcnt(14)
	v_mfma_f32_32x32x16_bf16 v[34:49], v[154:157], v[106:109], v[34:49]
	v_exp_f32_e32 v130, v130
	v_exp_f32_e32 v131, v131
	v_exp_f32_e32 v132, v132
	ds_read_b64_tr_b16 v[106:107], v216 offset:37888
	ds_read_b64_tr_b16 v[108:109], v216 offset:38400
	ds_read_b128 v[202:205], v178 offset:2048
	ds_read_b128 v[190:193], v178 offset:2560
	v_mfma_f32_32x32x16_bf16 v[50:65], v[150:153], v[102:105], v[50:65]
	v_exp_f32_e32 v133, v133
	v_exp_f32_e32 v134, v134
	v_exp_f32_e32 v135, v135
	ds_read_b64_tr_b16 v[102:103], v216 offset:34816
	ds_read_b64_tr_b16 v[104:105], v216 offset:35328
	ds_read_b128 v[194:197], v178 offset:4096
	ds_read_b128 v[182:185], v178 offset:4608
	s_waitcnt lgkmcnt(14)
	v_mfma_f32_32x32x16_bf16 v[34:49], v[150:153], v[98:101], v[34:49]
	v_exp_f32_e32 v136, v136
	v_exp_f32_e32 v137, v137
	v_exp_f32_e32 v138, v138
	ds_read_b64_tr_b16 v[98:99], v216 offset:38912
	ds_read_b64_tr_b16 v[100:101], v216 offset:39424
	ds_read_b128 v[186:189], v178 offset:6144
	ds_read_b128 v[178:181], v178 offset:6656
	v_mfma_f32_32x32x16_bf16 v[50:65], v[146:149], v[86:89], v[50:65]
	v_exp_f32_e32 v139, v139
	v_exp_f32_e32 v140, v140
	v_exp_f32_e32 v141, v141
	ds_read_b64_tr_b16 v[86:87], v216 offset:35840
	ds_read_b64_tr_b16 v[88:89], v216 offset:36352
	v_mfma_f32_32x32x16_bf16 v[34:49], v[146:149], v[90:93], v[34:49]
	v_exp_f32_e32 v142, v142
	v_exp_f32_e32 v143, v143
	v_exp_f32_e32 v144, v144
	ds_read_b64_tr_b16 v[90:91], v216 offset:39936
	ds_read_b64_tr_b16 v[92:93], v216 offset:40448
	v_mfma_f32_32x32x16_bf16 v[18:33], v[158:161], v[206:209], v[18:33]
	v_exp_f32_e32 v145, v145
	v_exp_f32_e32 v114, v114
	v_exp_f32_e32 v115, v115
	s_waitcnt lgkmcnt(14)
	v_mfma_f32_32x32x16_bf16 v[2:17], v[158:161], v[110:113], v[2:17]
	v_exp_f32_e32 v116, v116
	v_exp_f32_e32 v117, v117
	v_mfma_f32_32x32x16_bf16 v[18:33], v[154:157], v[94:97], v[18:33]
	v_exp_f32_e32 v118, v118
	v_exp_f32_e32 v119, v119
	v_mfma_f32_32x32x16_bf16 v[2:17], v[154:157], v[106:109], v[2:17]
	v_exp_f32_e32 v120, v120
	v_exp_f32_e32 v121, v121
	s_waitcnt lgkmcnt(10)
	v_mfma_f32_32x32x16_bf16 v[18:33], v[150:153], v[102:105], v[18:33]
	v_exp_f32_e32 v122, v122
	v_exp_f32_e32 v123, v123
	s_waitcnt lgkmcnt(6)
	v_mfma_f32_32x32x16_bf16 v[2:17], v[150:153], v[98:101], v[2:17]
	v_exp_f32_e32 v124, v124
	v_exp_f32_e32 v125, v125
	s_waitcnt lgkmcnt(2)
	v_mfma_f32_32x32x16_bf16 v[18:33], v[146:149], v[86:89], v[18:33]
	v_exp_f32_e32 v126, v126
	v_exp_f32_e32 v127, v127
	s_waitcnt lgkmcnt(0)
	v_mfma_f32_32x32x16_bf16 v[2:17], v[146:149], v[90:93], v[2:17]
	v_exp_f32_e32 v128, v128
	v_exp_f32_e32 v129, v129
	s_waitcnt vmcnt(3) lgkmcnt(0)
	s_barrier
	s_andn2_b64 vcc, exec, s[86:87]
	s_cbranch_vccnz .LBB0_1129
	s_waitcnt lgkmcnt(0)
	v_add_u32_e32 v98, s3, v245
	ds_read_b128 v[86:89], v98 offset:96
	ds_read_b128 v[90:93], v98 offset:64
	ds_read_b128 v[94:97], v98 offset:32
	ds_read_b128 v[98:101], v98
	s_waitcnt lgkmcnt(3)
	v_pk_mul_f32 v[62:63], v[62:63], v[86:87]
	s_waitcnt lgkmcnt(2)
	v_pk_mul_f32 v[58:59], v[58:59], v[90:91]
	s_waitcnt lgkmcnt(1)
	v_pk_mul_f32 v[54:55], v[54:55], v[94:95]
	v_pk_mul_f32 v[64:65], v[64:65], v[88:89]
	v_pk_mul_f32 v[60:61], v[60:61], v[92:93]
	v_pk_mul_f32 v[56:57], v[56:57], v[96:97]
	s_waitcnt lgkmcnt(0)
	v_pk_mul_f32 v[52:53], v[52:53], v[100:101]
	v_pk_mul_f32 v[50:51], v[50:51], v[98:99]
	v_pk_mul_f32 v[46:47], v[46:47], v[86:87]
	v_pk_mul_f32 v[42:43], v[42:43], v[90:91]
	v_pk_mul_f32 v[38:39], v[38:39], v[94:95]
	v_pk_mul_f32 v[48:49], v[48:49], v[88:89]
	v_pk_mul_f32 v[44:45], v[44:45], v[92:93]
	v_pk_mul_f32 v[40:41], v[40:41], v[96:97]
	v_pk_mul_f32 v[36:37], v[36:37], v[100:101]
	v_pk_mul_f32 v[34:35], v[34:35], v[98:99]
	v_pk_mul_f32 v[30:31], v[30:31], v[86:87]
	v_pk_mul_f32 v[26:27], v[26:27], v[90:91]
	v_pk_mul_f32 v[22:23], v[22:23], v[94:95]
	v_pk_mul_f32 v[32:33], v[32:33], v[88:89]
	v_pk_mul_f32 v[28:29], v[28:29], v[92:93]
	v_pk_mul_f32 v[24:25], v[24:25], v[96:97]
	v_pk_mul_f32 v[20:21], v[20:21], v[100:101]
	v_pk_mul_f32 v[18:19], v[18:19], v[98:99]
	v_pk_mul_f32 v[14:15], v[14:15], v[86:87]
	v_pk_mul_f32 v[10:11], v[10:11], v[90:91]
	v_pk_mul_f32 v[6:7], v[6:7], v[94:95]
	v_pk_mul_f32 v[16:17], v[16:17], v[88:89]
	v_pk_mul_f32 v[12:13], v[12:13], v[92:93]
	v_pk_mul_f32 v[8:9], v[8:9], v[96:97]
	v_pk_mul_f32 v[4:5], v[4:5], v[100:101]
	v_pk_mul_f32 v[2:3], v[2:3], v[98:99]
.LBB0_1129:
	s_add_i32 s4, s84, 0x2000
	s_cmpk_lg_i32 s84, 0x4000
	s_cselect_b32 s4, s4, 0
	s_lshl_b32 s8, s15, 1
	v_add_u32_e32 v226, s8, v247
	ds_read_b64_tr_b16 v[206:207], v226 offset:24576
	ds_read_b64_tr_b16 v[208:209], v226 offset:25088
	v_mfma_f32_32x32x16_bf16 v[98:113], v[82:85], v[174:177], v[66:81]
	v_add_f32_e32 v86, v130, v131
	v_add_f32_e32 v86, v132, v86
	v_add_f32_e32 v86, v133, v86
	v_add_f32_e32 v86, v134, v86
	v_add_f32_e32 v86, v135, v86
	v_cvt_pk_bf16_f32 v158, v130, v131
	v_cvt_pk_bf16_f32 v159, v132, v133
	ds_read_b64_tr_b16 v[250:251], v226 offset:28672
	ds_read_b64_tr_b16 v[252:253], v226 offset:29184
	v_add_f32_e32 v82, v136, v86
	v_add_f32_e32 v82, v137, v82
	v_add_f32_e32 v82, v138, v82
	v_add_f32_e32 v130, v139, v82
	v_mfma_f32_32x32x16_bf16 v[82:97], v[198:201], v[174:177], v[66:81]
	v_cvt_pk_bf16_f32 v160, v134, v135
	v_cvt_pk_bf16_f32 v161, v136, v137
	ds_read_b64_tr_b16 v[198:199], v226 offset:25600
	ds_read_b64_tr_b16 v[200:201], v226 offset:26112
	v_mfma_f32_32x32x16_bf16 v[98:113], v[202:205], v[170:173], v[98:113]
	v_add_f32_e32 v130, v140, v130
	v_add_f32_e32 v130, v141, v130
	v_add_f32_e32 v130, v142, v130
	v_add_f32_e32 v130, v143, v130
	v_cvt_pk_bf16_f32 v154, v138, v139
	v_cvt_pk_bf16_f32 v155, v140, v141
	ds_read_b64_tr_b16 v[138:139], v226 offset:29696
	ds_read_b64_tr_b16 v[140:141], v226 offset:30208
	v_mfma_f32_32x32x16_bf16 v[82:97], v[190:193], v[170:173], v[82:97]
	v_add_f32_e32 v130, v144, v130
	v_add_f32_e32 v130, v145, v130
	v_add_f32_e32 v130, v114, v130
	v_add_f32_e32 v130, v115, v130
	v_cvt_pk_bf16_f32 v156, v142, v143
	v_cvt_pk_bf16_f32 v157, v144, v145
	ds_read_b64_tr_b16 v[134:135], v226 offset:26624
	ds_read_b64_tr_b16 v[136:137], v226 offset:27136
	v_mfma_f32_32x32x16_bf16 v[98:113], v[194:197], v[166:169], v[98:113]
	v_add_f32_e32 v130, v116, v130
	v_add_f32_e32 v130, v117, v130
	v_add_f32_e32 v130, v118, v130
	v_add_f32_e32 v142, v119, v130
	v_cvt_pk_bf16_f32 v150, v114, v115
	v_cvt_pk_bf16_f32 v151, v116, v117
	ds_read_b64_tr_b16 v[130:131], v226 offset:30720
	ds_read_b64_tr_b16 v[132:133], v226 offset:31232
	v_mfma_f32_32x32x16_bf16 v[82:97], v[182:185], v[166:169], v[82:97]
	v_add_f32_e32 v114, v120, v142
	v_add_f32_e32 v114, v121, v114
	v_add_f32_e32 v114, v122, v114
	v_add_f32_e32 v142, v123, v114
	v_cvt_pk_bf16_f32 v152, v118, v119
	v_cvt_pk_bf16_f32 v153, v120, v121
	ds_read_b64_tr_b16 v[114:115], v226 offset:27648
	ds_read_b64_tr_b16 v[116:117], v226 offset:28160
	v_mfma_f32_32x32x16_bf16 v[98:113], v[186:189], v[162:165], v[98:113]
	v_add_f32_e32 v118, v124, v142
	v_add_f32_e32 v118, v125, v118
	v_add_f32_e32 v118, v126, v118
	v_add_f32_e32 v142, v127, v118
	v_cvt_pk_bf16_f32 v146, v122, v123
	v_cvt_pk_bf16_f32 v147, v124, v125
	ds_read_b64_tr_b16 v[118:119], v226 offset:31744
	ds_read_b64_tr_b16 v[120:121], v226 offset:32256
	v_mfma_f32_32x32x16_bf16 v[82:97], v[178:181], v[162:165], v[82:97]
	v_add_f32_e32 v122, v128, v142
	v_add_f32_e32 v122, v129, v122
	v_add_f32_e32 v178, 0, v122
	v_cvt_pk_bf16_f32 v148, v126, v127
	v_cvt_pk_bf16_f32 v149, v128, v129
	s_mov_b64 s[8:9], 0x180000
	v_lshl_add_u64 v[122:123], v[212:213], 0, s[8:9]
	s_add_i32 s8, s84, s55
	s_mov_b32 s9, m0
	s_mov_b32 m0, s8
	s_nop 0
	global_load_lds_dwordx4 v[122:123], off
	s_mov_b32 m0, s9
	s_lshl_b32 s8, s4, 1
	s_waitcnt lgkmcnt(14)
	v_mfma_f32_32x32x16_bf16 v[50:65], v[158:161], v[206:209], v[50:65]
	v_lshl_add_u64 v[216:217], v[214:215], 0, s[60:61]
	s_add_i32 s8, s8, s1
	s_mov_b32 s9, m0
	s_mov_b32 m0, s8
	s_nop 0
	global_load_lds_dwordx4 v[216:217], off
	s_mov_b32 m0, s9
	v_lshl_add_u64 v[122:123], v[214:215], 0, s[66:67]
	s_addk_i32 s8, 0x2000
	s_mov_b32 s9, m0
	s_mov_b32 m0, s8
	s_nop 0
	global_load_lds_dwordx4 v[122:123], off
	s_mov_b32 m0, s9
	ds_read_b64_tr_b16 v[142:143], v226 offset:32768
	ds_read_b64_tr_b16 v[144:145], v226 offset:33280
	s_waitcnt lgkmcnt(14)
	v_mfma_f32_32x32x16_bf16 v[34:49], v[158:161], v[250:253], v[34:49]
	ds_read_b64_tr_b16 v[126:127], v226 offset:36864
	ds_read_b64_tr_b16 v[128:129], v226 offset:37376
	s_waitcnt lgkmcnt(14)
	v_mfma_f32_32x32x16_bf16 v[50:65], v[154:157], v[198:201], v[50:65]
	ds_read_b64_tr_b16 v[122:123], v226 offset:33792
	ds_read_b64_tr_b16 v[124:125], v226 offset:34304
	v_max_f32_e32 v179, v98, v99
	v_max3_f32 v180, v100, v101, v83
	v_max3_f32 v179, v179, v82, v84
	v_max3_f32 v179, v179, v85, v102
	v_max3_f32 v180, v180, v104, v105
	v_max3_f32 v179, v179, v103, v86
	v_max3_f32 v180, v180, v88, v89
	v_max3_f32 v179, v179, v87, v106
	v_max3_f32 v180, v180, v108, v109
	v_max3_f32 v179, v179, v107, v90
	v_max3_f32 v180, v180, v92, v93
	v_max3_f32 v179, v179, v91, v110
	v_max3_f32 v180, v180, v112, v113
	v_max3_f32 v179, v179, v111, v94
	v_max3_f32 v180, v180, v96, v97
	v_add_f32_e32 v249, v1, v178
	v_max3_f32 v1, v179, v95, v180
	v_mov_b32_e32 v178, v1
	s_nop 1
	v_permlane32_swap_b32_e32 v1, v178
	v_max_f32_e32 v1, v1, v178
	v_cmp_lt_f32_e32 vcc, s13, v1
	s_cmp_lg_u64 vcc, 0
	s_cselect_b64 s[86:87], -1, 0
	s_cbranch_vccnz .LBB0_1137
.LBB0_1130:
	v_add_u32_e32 v1, s4, v248
	ds_read_b128 v[206:209], v1
	ds_read_b128 v[198:201], v1 offset:512
	s_waitcnt lgkmcnt(14)
	v_mfma_f32_32x32x16_bf16 v[34:49], v[154:157], v[138:141], v[34:49]
	v_exp_f32_e32 v98, v98
	v_exp_f32_e32 v99, v99
	v_exp_f32_e32 v100, v100
	ds_read_b64_tr_b16 v[138:139], v226 offset:37888
	ds_read_b64_tr_b16 v[140:141], v226 offset:38400
	ds_read_b128 v[202:205], v1 offset:2048
	ds_read_b128 v[194:197], v1 offset:2560
	v_mfma_f32_32x32x16_bf16 v[50:65], v[150:153], v[134:137], v[50:65]
	v_exp_f32_e32 v101, v101
	v_exp_f32_e32 v102, v102
	v_exp_f32_e32 v103, v103
	ds_read_b64_tr_b16 v[134:135], v226 offset:34816
	ds_read_b64_tr_b16 v[136:137], v226 offset:35328
	ds_read_b128 v[190:193], v1 offset:4096
	ds_read_b128 v[186:189], v1 offset:4608
	s_waitcnt lgkmcnt(14)
	v_mfma_f32_32x32x16_bf16 v[34:49], v[150:153], v[130:133], v[34:49]
	v_exp_f32_e32 v104, v104
	v_exp_f32_e32 v105, v105
	v_exp_f32_e32 v106, v106
	ds_read_b64_tr_b16 v[130:131], v226 offset:38912
	ds_read_b64_tr_b16 v[132:133], v226 offset:39424
	ds_read_b128 v[182:185], v1 offset:6144
	ds_read_b128 v[178:181], v1 offset:6656
	v_mfma_f32_32x32x16_bf16 v[50:65], v[146:149], v[114:117], v[50:65]
	v_exp_f32_e32 v107, v107
	v_exp_f32_e32 v108, v108
	v_exp_f32_e32 v109, v109
	ds_read_b64_tr_b16 v[114:115], v226 offset:35840
	ds_read_b64_tr_b16 v[116:117], v226 offset:36352
	v_mfma_f32_32x32x16_bf16 v[34:49], v[146:149], v[118:121], v[34:49]
	v_exp_f32_e32 v110, v110
	v_exp_f32_e32 v111, v111
	v_exp_f32_e32 v112, v112
	ds_read_b64_tr_b16 v[118:119], v226 offset:39936
	ds_read_b64_tr_b16 v[120:121], v226 offset:40448
	v_mfma_f32_32x32x16_bf16 v[18:33], v[158:161], v[142:145], v[18:33]
	v_exp_f32_e32 v113, v113
	v_exp_f32_e32 v82, v82
	v_exp_f32_e32 v83, v83
	s_waitcnt lgkmcnt(14)
	v_mfma_f32_32x32x16_bf16 v[2:17], v[158:161], v[126:129], v[2:17]
	v_exp_f32_e32 v84, v84
	v_exp_f32_e32 v85, v85
	v_mfma_f32_32x32x16_bf16 v[18:33], v[154:157], v[122:125], v[18:33]
	v_exp_f32_e32 v86, v86
	v_exp_f32_e32 v87, v87
	v_mfma_f32_32x32x16_bf16 v[2:17], v[154:157], v[138:141], v[2:17]
	v_exp_f32_e32 v88, v88
	v_exp_f32_e32 v89, v89
	s_waitcnt lgkmcnt(10)
	v_mfma_f32_32x32x16_bf16 v[18:33], v[150:153], v[134:137], v[18:33]
	v_exp_f32_e32 v90, v90
	v_exp_f32_e32 v91, v91
	s_waitcnt lgkmcnt(6)
	v_mfma_f32_32x32x16_bf16 v[2:17], v[150:153], v[130:133], v[2:17]
	v_exp_f32_e32 v92, v92
	v_exp_f32_e32 v93, v93
	s_waitcnt lgkmcnt(2)
	v_mfma_f32_32x32x16_bf16 v[18:33], v[146:149], v[114:117], v[18:33]
	v_exp_f32_e32 v94, v94
	v_exp_f32_e32 v95, v95
	s_waitcnt lgkmcnt(0)
	v_mfma_f32_32x32x16_bf16 v[2:17], v[146:149], v[118:121], v[2:17]
	v_exp_f32_e32 v96, v96
	v_exp_f32_e32 v97, v97
	s_waitcnt vmcnt(3) lgkmcnt(0)
	s_barrier
	s_andn2_b64 vcc, exec, s[86:87]
	s_cbranch_vccnz .LBB0_1132
	s_waitcnt lgkmcnt(0)
	v_add_u32_e32 v1, s3, v245
	ds_read_b128 v[114:117], v1 offset:96
	ds_read_b128 v[118:121], v1 offset:64
	ds_read_b128 v[122:125], v1 offset:32
	ds_read_b128 v[126:129], v1
	s_waitcnt lgkmcnt(3)
	v_pk_mul_f32 v[62:63], v[62:63], v[114:115]
	s_waitcnt lgkmcnt(2)
	v_pk_mul_f32 v[58:59], v[58:59], v[118:119]
	s_waitcnt lgkmcnt(1)
	v_pk_mul_f32 v[54:55], v[54:55], v[122:123]
	v_pk_mul_f32 v[64:65], v[64:65], v[116:117]
	v_pk_mul_f32 v[60:61], v[60:61], v[120:121]
	v_pk_mul_f32 v[56:57], v[56:57], v[124:125]
	s_waitcnt lgkmcnt(0)
	v_pk_mul_f32 v[52:53], v[52:53], v[128:129]
	v_pk_mul_f32 v[50:51], v[50:51], v[126:127]
	v_pk_mul_f32 v[46:47], v[46:47], v[114:115]
	v_pk_mul_f32 v[42:43], v[42:43], v[118:119]
	v_pk_mul_f32 v[38:39], v[38:39], v[122:123]
	v_pk_mul_f32 v[48:49], v[48:49], v[116:117]
	v_pk_mul_f32 v[44:45], v[44:45], v[120:121]
	v_pk_mul_f32 v[40:41], v[40:41], v[124:125]
	v_pk_mul_f32 v[36:37], v[36:37], v[128:129]
	v_pk_mul_f32 v[34:35], v[34:35], v[126:127]
	v_pk_mul_f32 v[30:31], v[30:31], v[114:115]
	v_pk_mul_f32 v[26:27], v[26:27], v[118:119]
	v_pk_mul_f32 v[22:23], v[22:23], v[122:123]
	v_pk_mul_f32 v[32:33], v[32:33], v[116:117]
	v_pk_mul_f32 v[28:29], v[28:29], v[120:121]
	v_pk_mul_f32 v[24:25], v[24:25], v[124:125]
	v_pk_mul_f32 v[20:21], v[20:21], v[128:129]
	v_pk_mul_f32 v[18:19], v[18:19], v[126:127]
	v_pk_mul_f32 v[14:15], v[14:15], v[114:115]
	v_pk_mul_f32 v[10:11], v[10:11], v[118:119]
	v_pk_mul_f32 v[6:7], v[6:7], v[122:123]
	v_pk_mul_f32 v[16:17], v[16:17], v[116:117]
	v_pk_mul_f32 v[12:13], v[12:13], v[120:121]
	v_pk_mul_f32 v[8:9], v[8:9], v[124:125]
	v_pk_mul_f32 v[4:5], v[4:5], v[128:129]
	v_pk_mul_f32 v[2:3], v[2:3], v[126:127]

.LBB0_1141:
	s_lshl_b32 s9, s84, 1
	v_add_u32_e32 v250, s9, v247
	ds_read_b64_tr_b16 v[210:211], v250 offset:24576
	ds_read_b64_tr_b16 v[212:213], v250 offset:25088
	v_mfma_f32_32x32x16_bf16 v[130:145], v[206:209], v[174:177], v[66:81]
	v_add_f32_e32 v1, v98, v99
	v_add_f32_e32 v1, v100, v1
	v_add_f32_e32 v1, v101, v1
	v_add_f32_e32 v1, v102, v1
	v_add_f32_e32 v1, v103, v1
	v_cvt_pk_bf16_f32 v158, v98, v99
	v_cvt_pk_bf16_f32 v159, v100, v101
	ds_read_b64_tr_b16 v[214:215], v250 offset:28672
	ds_read_b64_tr_b16 v[216:217], v250 offset:29184
	v_mfma_f32_32x32x16_bf16 v[114:129], v[198:201], v[174:177], v[66:81]
	v_add_f32_e32 v1, v104, v1
	v_add_f32_e32 v1, v105, v1
	v_add_f32_e32 v1, v106, v1
	v_add_f32_e32 v1, v107, v1
	v_cvt_pk_bf16_f32 v160, v102, v103
	v_cvt_pk_bf16_f32 v161, v104, v105
	ds_read_b64_tr_b16 v[198:199], v250 offset:25600
	ds_read_b64_tr_b16 v[200:201], v250 offset:26112
	v_mfma_f32_32x32x16_bf16 v[130:145], v[202:205], v[170:173], v[130:145]
	v_add_f32_e32 v1, v108, v1
	v_add_f32_e32 v1, v109, v1
	v_add_f32_e32 v1, v110, v1
	v_add_f32_e32 v1, v111, v1
	v_cvt_pk_bf16_f32 v154, v106, v107
	v_cvt_pk_bf16_f32 v155, v108, v109
	ds_read_b64_tr_b16 v[106:107], v250 offset:29696
	ds_read_b64_tr_b16 v[108:109], v250 offset:30208
	v_mfma_f32_32x32x16_bf16 v[114:129], v[194:197], v[170:173], v[114:129]
	v_add_f32_e32 v1, v112, v1
	v_add_f32_e32 v1, v113, v1
	v_add_f32_e32 v1, v82, v1
	v_add_f32_e32 v1, v83, v1
	v_cvt_pk_bf16_f32 v156, v110, v111
	v_cvt_pk_bf16_f32 v157, v112, v113
	ds_read_b64_tr_b16 v[102:103], v250 offset:26624
	ds_read_b64_tr_b16 v[104:105], v250 offset:27136
	v_mfma_f32_32x32x16_bf16 v[130:145], v[190:193], v[166:169], v[130:145]
	v_add_f32_e32 v1, v84, v1
	v_add_f32_e32 v1, v85, v1
	v_add_f32_e32 v1, v86, v1
	v_add_f32_e32 v1, v87, v1
	v_cvt_pk_bf16_f32 v150, v82, v83
	v_cvt_pk_bf16_f32 v151, v84, v85
	ds_read_b64_tr_b16 v[98:99], v250 offset:30720
	ds_read_b64_tr_b16 v[100:101], v250 offset:31232
	v_mfma_f32_32x32x16_bf16 v[114:129], v[186:189], v[166:169], v[114:129]
	v_add_f32_e32 v1, v88, v1
	v_add_f32_e32 v1, v89, v1
	v_add_f32_e32 v1, v90, v1
	v_add_f32_e32 v1, v91, v1
	v_cvt_pk_bf16_f32 v152, v86, v87
	v_cvt_pk_bf16_f32 v153, v88, v89
	ds_read_b64_tr_b16 v[86:87], v250 offset:27648
	ds_read_b64_tr_b16 v[88:89], v250 offset:28160
	v_mfma_f32_32x32x16_bf16 v[130:145], v[182:185], v[162:165], v[130:145]
	v_add_f32_e32 v1, v92, v1
	v_add_f32_e32 v1, v93, v1
	v_add_f32_e32 v1, v94, v1
	v_add_f32_e32 v1, v95, v1
	v_cvt_pk_bf16_f32 v146, v90, v91
	v_cvt_pk_bf16_f32 v147, v92, v93
	ds_read_b64_tr_b16 v[90:91], v250 offset:31744
	ds_read_b64_tr_b16 v[92:93], v250 offset:32256
	v_mfma_f32_32x32x16_bf16 v[114:129], v[178:181], v[162:165], v[114:129]
	v_add_f32_e32 v1, v96, v1
	v_add_f32_e32 v1, v97, v1
	v_cvt_pk_bf16_f32 v148, v94, v95
	v_cvt_pk_bf16_f32 v149, v96, v97
	s_cmpk_gt_u32 s15, 0x80
	s_cselect_b64 s[88:89], -1, 0
	s_and_b64 vcc, exec, s[88:89]
	s_mov_b64 s[90:91], s[86:87]
	s_cbranch_vccnz .LBB0_1143
	s_add_i32 s9, s4, s55
	v_lshl_add_u64 v[82:83], v[226:227], 0, s[62:63]
	s_mov_b32 s33, m0
	s_mov_b32 m0, s9
	s_nop 0
	global_load_lds_dwordx4 v[82:83], off
	s_mov_b32 m0, s33
	s_mul_i32 s84, s15, 0x30000
	s_mov_b64 s[90:91], s[84:85]
.LBB0_1143:
	v_lshl_add_u64 v[228:229], s[90:91], 1, v[224:225]
	s_lshl_b32 s33, s8, 1
	s_waitcnt lgkmcnt(14)
	v_mfma_f32_32x32x16_bf16 v[50:65], v[158:161], v[210:213], v[50:65]
	v_lshl_add_u64 v[82:83], v[228:229], 0, s[58:59]
	s_add_i32 s9, s33, s1
	s_mov_b32 s84, m0
	s_mov_b32 m0, s9
	s_nop 0
	global_load_lds_dwordx4 v[82:83], off
	s_mov_b32 m0, s84
	v_lshl_add_u64 v[82:83], v[228:229], 0, s[64:65]
	s_addk_i32 s9, 0x2000
	s_mov_b32 s84, m0
	s_mov_b32 m0, s9
	s_nop 0
	global_load_lds_dwordx4 v[82:83], off
	s_mov_b32 m0, s84
	ds_read_b64_tr_b16 v[206:207], v250 offset:32768
	ds_read_b64_tr_b16 v[208:209], v250 offset:33280
	v_add_f32_e32 v1, v249, v1
	s_waitcnt lgkmcnt(14)
	v_mfma_f32_32x32x16_bf16 v[34:49], v[158:161], v[214:217], v[34:49]
	ds_read_b64_tr_b16 v[110:111], v250 offset:36864
	ds_read_b64_tr_b16 v[112:113], v250 offset:37376
	s_waitcnt lgkmcnt(14)
	v_mfma_f32_32x32x16_bf16 v[50:65], v[154:157], v[198:201], v[50:65]
	ds_read_b64_tr_b16 v[94:95], v250 offset:33792
	ds_read_b64_tr_b16 v[96:97], v250 offset:34304
	v_max_f32_e32 v82, v130, v131
	v_max3_f32 v83, v132, v133, v115
	v_max3_f32 v82, v82, v114, v116
	v_max3_f32 v82, v82, v117, v134
	v_max3_f32 v83, v83, v136, v137
	v_max3_f32 v82, v82, v135, v118
	v_max3_f32 v83, v83, v120, v121
	v_max3_f32 v82, v82, v119, v138
	v_max3_f32 v83, v83, v140, v141
	v_max3_f32 v82, v82, v139, v122
	v_max3_f32 v83, v83, v124, v125
	v_max3_f32 v82, v82, v123, v142
	v_max3_f32 v83, v83, v144, v145
	v_max3_f32 v82, v82, v143, v126
	v_max3_f32 v83, v83, v128, v129
	v_max3_f32 v82, v82, v127, v83
	v_mov_b32_e32 v83, v82
	s_nop 1
	v_permlane32_swap_b32_e32 v82, v83
	v_max_f32_e32 v82, v82, v83
	v_cmp_lt_f32_e32 vcc, s13, v82
	s_cmp_lg_u64 vcc, 0
	s_cselect_b64 s[92:93], -1, 0
	s_cbranch_vccnz .LBB0_1161
.LBB0_1144:
	v_add_u32_e32 v178, s8, v248
	ds_read_b128 v[82:85], v178
	ds_read_b128 v[198:201], v178 offset:512
	s_waitcnt lgkmcnt(14)
	v_mfma_f32_32x32x16_bf16 v[34:49], v[154:157], v[106:109], v[34:49]
	v_exp_f32_e32 v130, v130
	v_exp_f32_e32 v131, v131
	v_exp_f32_e32 v132, v132
	ds_read_b64_tr_b16 v[106:107], v250 offset:37888
	ds_read_b64_tr_b16 v[108:109], v250 offset:38400
	ds_read_b128 v[202:205], v178 offset:2048
	ds_read_b128 v[190:193], v178 offset:2560
	v_mfma_f32_32x32x16_bf16 v[50:65], v[150:153], v[102:105], v[50:65]
	v_exp_f32_e32 v133, v133
	v_exp_f32_e32 v134, v134
	v_exp_f32_e32 v135, v135
	ds_read_b64_tr_b16 v[102:103], v250 offset:34816
	ds_read_b64_tr_b16 v[104:105], v250 offset:35328
	ds_read_b128 v[194:197], v178 offset:4096
	ds_read_b128 v[182:185], v178 offset:4608
	s_waitcnt lgkmcnt(14)
	v_mfma_f32_32x32x16_bf16 v[34:49], v[150:153], v[98:101], v[34:49]
	v_exp_f32_e32 v136, v136
	v_exp_f32_e32 v137, v137
	v_exp_f32_e32 v138, v138
	ds_read_b64_tr_b16 v[98:99], v250 offset:38912
	ds_read_b64_tr_b16 v[100:101], v250 offset:39424
	ds_read_b128 v[186:189], v178 offset:6144
	ds_read_b128 v[178:181], v178 offset:6656
	v_mfma_f32_32x32x16_bf16 v[50:65], v[146:149], v[86:89], v[50:65]
	v_exp_f32_e32 v139, v139
	v_exp_f32_e32 v140, v140
	v_exp_f32_e32 v141, v141
	ds_read_b64_tr_b16 v[86:87], v250 offset:35840
	ds_read_b64_tr_b16 v[88:89], v250 offset:36352
	v_mfma_f32_32x32x16_bf16 v[34:49], v[146:149], v[90:93], v[34:49]
	v_exp_f32_e32 v142, v142
	v_exp_f32_e32 v143, v143
	v_exp_f32_e32 v144, v144
	ds_read_b64_tr_b16 v[90:91], v250 offset:39936
	ds_read_b64_tr_b16 v[92:93], v250 offset:40448
	v_mfma_f32_32x32x16_bf16 v[18:33], v[158:161], v[206:209], v[18:33]
	v_exp_f32_e32 v145, v145
	v_exp_f32_e32 v114, v114
	v_exp_f32_e32 v115, v115
	s_waitcnt lgkmcnt(14)
	v_mfma_f32_32x32x16_bf16 v[2:17], v[158:161], v[110:113], v[2:17]
	v_exp_f32_e32 v116, v116
	v_exp_f32_e32 v117, v117
	v_mfma_f32_32x32x16_bf16 v[18:33], v[154:157], v[94:97], v[18:33]
	v_exp_f32_e32 v118, v118
	v_exp_f32_e32 v119, v119
	v_mfma_f32_32x32x16_bf16 v[2:17], v[154:157], v[106:109], v[2:17]
	v_exp_f32_e32 v120, v120
	v_exp_f32_e32 v121, v121
	s_waitcnt lgkmcnt(10)
	v_mfma_f32_32x32x16_bf16 v[18:33], v[150:153], v[102:105], v[18:33]
	v_exp_f32_e32 v122, v122
	v_exp_f32_e32 v123, v123
	s_waitcnt lgkmcnt(6)
	v_mfma_f32_32x32x16_bf16 v[2:17], v[150:153], v[98:101], v[2:17]
	v_exp_f32_e32 v124, v124
	v_exp_f32_e32 v125, v125
	s_waitcnt lgkmcnt(2)
	v_mfma_f32_32x32x16_bf16 v[18:33], v[146:149], v[86:89], v[18:33]
	v_exp_f32_e32 v126, v126
	v_exp_f32_e32 v127, v127
	s_waitcnt lgkmcnt(0)
	v_mfma_f32_32x32x16_bf16 v[2:17], v[146:149], v[90:93], v[2:17]
	v_exp_f32_e32 v128, v128
	v_exp_f32_e32 v129, v129
	s_mov_b64 s[94:95], -1
	s_and_b64 vcc, exec, s[88:89]
	s_cbranch_vccz .LBB0_1157
	s_waitcnt vmcnt(2) lgkmcnt(0)
	s_barrier
	s_cbranch_execz .LBB0_1158

.LBB0_1148:
	s_lshl_b32 s4, s4, 1
	v_add_u32_e32 v214, s4, v247
	ds_read_b64_tr_b16 v[206:207], v214 offset:24576
	ds_read_b64_tr_b16 v[208:209], v214 offset:25088
	v_mfma_f32_32x32x16_bf16 v[98:113], v[82:85], v[174:177], v[66:81]
	v_add_f32_e32 v86, v130, v131
	v_add_f32_e32 v86, v132, v86
	v_add_f32_e32 v86, v133, v86
	v_add_f32_e32 v86, v134, v86
	v_add_f32_e32 v86, v135, v86
	v_cvt_pk_bf16_f32 v158, v130, v131
	v_cvt_pk_bf16_f32 v159, v132, v133
	ds_read_b64_tr_b16 v[210:211], v214 offset:28672
	ds_read_b64_tr_b16 v[212:213], v214 offset:29184
	v_add_f32_e32 v82, v136, v86
	v_add_f32_e32 v82, v137, v82
	v_add_f32_e32 v82, v138, v82
	v_add_f32_e32 v130, v139, v82
	v_mfma_f32_32x32x16_bf16 v[82:97], v[198:201], v[174:177], v[66:81]
	v_cvt_pk_bf16_f32 v160, v134, v135
	v_cvt_pk_bf16_f32 v161, v136, v137
	ds_read_b64_tr_b16 v[198:199], v214 offset:25600
	ds_read_b64_tr_b16 v[200:201], v214 offset:26112
	v_mfma_f32_32x32x16_bf16 v[98:113], v[202:205], v[170:173], v[98:113]
	v_add_f32_e32 v130, v140, v130
	v_add_f32_e32 v130, v141, v130
	v_add_f32_e32 v130, v142, v130
	v_add_f32_e32 v130, v143, v130
	v_cvt_pk_bf16_f32 v154, v138, v139
	v_cvt_pk_bf16_f32 v155, v140, v141
	ds_read_b64_tr_b16 v[138:139], v214 offset:29696
	ds_read_b64_tr_b16 v[140:141], v214 offset:30208
	v_mfma_f32_32x32x16_bf16 v[82:97], v[190:193], v[170:173], v[82:97]
	v_add_f32_e32 v130, v144, v130
	v_add_f32_e32 v130, v145, v130
	v_add_f32_e32 v130, v114, v130
	v_add_f32_e32 v130, v115, v130
	v_cvt_pk_bf16_f32 v156, v142, v143
	v_cvt_pk_bf16_f32 v157, v144, v145
	ds_read_b64_tr_b16 v[134:135], v214 offset:26624
	ds_read_b64_tr_b16 v[136:137], v214 offset:27136
	v_mfma_f32_32x32x16_bf16 v[98:113], v[194:197], v[166:169], v[98:113]
	v_add_f32_e32 v130, v116, v130
	v_add_f32_e32 v130, v117, v130
	v_add_f32_e32 v130, v118, v130
	v_add_f32_e32 v142, v119, v130
	v_cvt_pk_bf16_f32 v150, v114, v115
	v_cvt_pk_bf16_f32 v151, v116, v117
	ds_read_b64_tr_b16 v[130:131], v214 offset:30720
	ds_read_b64_tr_b16 v[132:133], v214 offset:31232
	v_mfma_f32_32x32x16_bf16 v[82:97], v[182:185], v[166:169], v[82:97]
	v_add_f32_e32 v114, v120, v142
	v_add_f32_e32 v114, v121, v114
	v_add_f32_e32 v114, v122, v114
	v_add_f32_e32 v142, v123, v114
	v_cvt_pk_bf16_f32 v152, v118, v119
	v_cvt_pk_bf16_f32 v153, v120, v121
	ds_read_b64_tr_b16 v[114:115], v214 offset:27648
	ds_read_b64_tr_b16 v[116:117], v214 offset:28160
	v_mfma_f32_32x32x16_bf16 v[98:113], v[186:189], v[162:165], v[98:113]
	v_add_f32_e32 v118, v124, v142
	v_add_f32_e32 v118, v125, v118
	v_add_f32_e32 v118, v126, v118
	v_add_f32_e32 v142, v127, v118
	v_cvt_pk_bf16_f32 v146, v122, v123
	v_cvt_pk_bf16_f32 v147, v124, v125
	ds_read_b64_tr_b16 v[118:119], v214 offset:31744
	ds_read_b64_tr_b16 v[120:121], v214 offset:32256
	v_mfma_f32_32x32x16_bf16 v[82:97], v[178:181], v[162:165], v[82:97]
	v_add_f32_e32 v122, v128, v142
	v_add_f32_e32 v122, v129, v122
	v_cvt_pk_bf16_f32 v148, v126, v127
	v_cvt_pk_bf16_f32 v149, v128, v129
	s_cmpk_gt_u32 s15, 0x7f
	s_cselect_b64 s[92:93], -1, 0
	s_and_b64 vcc, exec, s[92:93]
	s_cbranch_vccnz .LBB0_1150
	v_lshl_add_u64 v[124:125], s[90:91], 1, v[220:221]
	s_mov_b64 s[90:91], 0x180800
	s_add_i32 s4, s8, s55
	v_lshl_add_u64 v[124:125], v[124:125], 0, s[90:91]
	s_mov_b32 s9, m0
	s_mov_b32 m0, s4
	s_nop 0
	global_load_lds_dwordx4 v[124:125], off
	s_mov_b32 m0, s9
.LBB0_1150:
	s_add_i32 s4, s8, 0x2000
	s_cmpk_lg_i32 s8, 0x4000
	s_cselect_b32 s4, s4, 0
	s_lshl_b32 s84, s4, 1
	s_waitcnt lgkmcnt(14)
	v_mfma_f32_32x32x16_bf16 v[50:65], v[158:161], v[206:209], v[50:65]
	s_add_i32 s9, s84, s1
	v_lshl_add_u64 v[124:125], v[228:229], 0, s[60:61]
	s_mov_b32 s90, m0
	s_mov_b32 m0, s9
	s_nop 0
	global_load_lds_dwordx4 v[124:125], off
	s_mov_b32 m0, s90
	v_add_f32_e32 v249, v1, v122
	v_lshl_add_u64 v[122:123], v[228:229], 0, s[66:67]
	s_addk_i32 s9, 0x2000
	s_mov_b32 s90, m0
	s_mov_b32 m0, s9
	s_nop 0
	global_load_lds_dwordx4 v[122:123], off
	s_mov_b32 m0, s90
	ds_read_b64_tr_b16 v[142:143], v214 offset:32768
	ds_read_b64_tr_b16 v[144:145], v214 offset:33280
	s_waitcnt lgkmcnt(14)
	v_mfma_f32_32x32x16_bf16 v[34:49], v[158:161], v[210:213], v[34:49]
	ds_read_b64_tr_b16 v[126:127], v214 offset:36864
	ds_read_b64_tr_b16 v[128:129], v214 offset:37376
	s_waitcnt lgkmcnt(14)
	v_mfma_f32_32x32x16_bf16 v[50:65], v[154:157], v[198:201], v[50:65]
	ds_read_b64_tr_b16 v[122:123], v214 offset:33792
	ds_read_b64_tr_b16 v[124:125], v214 offset:34304
	v_max_f32_e32 v1, v98, v99
	v_max3_f32 v178, v100, v101, v83
	v_max3_f32 v1, v1, v82, v84
	v_max3_f32 v1, v1, v85, v102
	v_max3_f32 v178, v178, v104, v105
	v_max3_f32 v1, v1, v103, v86
	v_max3_f32 v178, v178, v88, v89
	v_max3_f32 v1, v1, v87, v106
	v_max3_f32 v178, v178, v108, v109
	v_max3_f32 v1, v1, v107, v90
	v_max3_f32 v178, v178, v92, v93
	v_max3_f32 v1, v1, v91, v110
	v_max3_f32 v178, v178, v112, v113
	v_max3_f32 v1, v1, v111, v94
	v_max3_f32 v178, v178, v96, v97
	v_max3_f32 v1, v1, v95, v178
	v_mov_b32_e32 v178, v1
	s_nop 1
	v_permlane32_swap_b32_e32 v1, v178
	v_max_f32_e32 v1, v1, v178
	v_cmp_lt_f32_e32 vcc, s13, v1
	s_cmp_lg_u64 vcc, 0
	s_cselect_b64 s[90:91], -1, 0
	s_cbranch_vccnz .LBB0_1164
.LBB0_1151:
	v_add_u32_e32 v1, s4, v248
	ds_read_b128 v[206:209], v1
	ds_read_b128 v[198:201], v1 offset:512
	s_waitcnt lgkmcnt(14)
	v_mfma_f32_32x32x16_bf16 v[34:49], v[154:157], v[138:141], v[34:49]
	v_exp_f32_e32 v98, v98
	v_exp_f32_e32 v99, v99
	v_exp_f32_e32 v100, v100
	ds_read_b64_tr_b16 v[138:139], v214 offset:37888
	ds_read_b64_tr_b16 v[140:141], v214 offset:38400
	ds_read_b128 v[202:205], v1 offset:2048
	ds_read_b128 v[194:197], v1 offset:2560
	v_mfma_f32_32x32x16_bf16 v[50:65], v[150:153], v[134:137], v[50:65]
	v_exp_f32_e32 v101, v101
	v_exp_f32_e32 v102, v102
	v_exp_f32_e32 v103, v103
	ds_read_b64_tr_b16 v[134:135], v214 offset:34816
	ds_read_b64_tr_b16 v[136:137], v214 offset:35328
	ds_read_b128 v[190:193], v1 offset:4096
	ds_read_b128 v[186:189], v1 offset:4608
	s_waitcnt lgkmcnt(14)
	v_mfma_f32_32x32x16_bf16 v[34:49], v[150:153], v[130:133], v[34:49]
	v_exp_f32_e32 v104, v104
	v_exp_f32_e32 v105, v105
	v_exp_f32_e32 v106, v106
	ds_read_b64_tr_b16 v[130:131], v214 offset:38912
	ds_read_b64_tr_b16 v[132:133], v214 offset:39424
	ds_read_b128 v[182:185], v1 offset:6144
	ds_read_b128 v[178:181], v1 offset:6656
	v_mfma_f32_32x32x16_bf16 v[50:65], v[146:149], v[114:117], v[50:65]
	v_exp_f32_e32 v107, v107
	v_exp_f32_e32 v108, v108
	v_exp_f32_e32 v109, v109
	ds_read_b64_tr_b16 v[114:115], v214 offset:35840
	ds_read_b64_tr_b16 v[116:117], v214 offset:36352
	v_mfma_f32_32x32x16_bf16 v[34:49], v[146:149], v[118:121], v[34:49]
	v_exp_f32_e32 v110, v110
	v_exp_f32_e32 v111, v111
	v_exp_f32_e32 v112, v112
	ds_read_b64_tr_b16 v[118:119], v214 offset:39936
	ds_read_b64_tr_b16 v[120:121], v214 offset:40448
	v_mfma_f32_32x32x16_bf16 v[18:33], v[158:161], v[142:145], v[18:33]
	v_exp_f32_e32 v113, v113
	v_exp_f32_e32 v82, v82
	v_exp_f32_e32 v83, v83
	s_waitcnt lgkmcnt(14)
	v_mfma_f32_32x32x16_bf16 v[2:17], v[158:161], v[126:129], v[2:17]
	v_exp_f32_e32 v84, v84
	v_exp_f32_e32 v85, v85
	v_mfma_f32_32x32x16_bf16 v[18:33], v[154:157], v[122:125], v[18:33]
	v_exp_f32_e32 v86, v86
	v_exp_f32_e32 v87, v87
	v_mfma_f32_32x32x16_bf16 v[2:17], v[154:157], v[138:141], v[2:17]
	v_exp_f32_e32 v88, v88
	v_exp_f32_e32 v89, v89
	s_waitcnt lgkmcnt(10)
	v_mfma_f32_32x32x16_bf16 v[18:33], v[150:153], v[134:137], v[18:33]
	v_exp_f32_e32 v90, v90
	v_exp_f32_e32 v91, v91
	s_waitcnt lgkmcnt(6)
	v_mfma_f32_32x32x16_bf16 v[2:17], v[150:153], v[130:133], v[2:17]
	v_exp_f32_e32 v92, v92
	v_exp_f32_e32 v93, v93
	s_waitcnt lgkmcnt(2)
	v_mfma_f32_32x32x16_bf16 v[18:33], v[146:149], v[114:117], v[18:33]
	v_exp_f32_e32 v94, v94
	v_exp_f32_e32 v95, v95
	s_waitcnt lgkmcnt(0)
	v_mfma_f32_32x32x16_bf16 v[2:17], v[146:149], v[118:121], v[2:17]
	v_exp_f32_e32 v96, v96
	v_exp_f32_e32 v97, v97
	s_mov_b64 s[94:95], -1
	s_and_b64 vcc, exec, s[92:93]
	s_cbranch_vccz .LBB0_1159
	s_waitcnt vmcnt(0) lgkmcnt(0)
	s_barrier
	s_cbranch_execz .LBB0_1160

.LBB0_1167:
	v_add_u32_e32 v210, s33, v247
	ds_read_b64_tr_b16 v[134:135], v210 offset:24576
	ds_read_b64_tr_b16 v[136:137], v210 offset:25088
	v_mfma_f32_32x32x16_bf16 v[114:129], v[206:209], v[174:177], v[66:81]
	v_add_f32_e32 v1, v98, v99
	v_add_f32_e32 v1, v100, v1
	v_add_f32_e32 v1, v101, v1
	v_add_f32_e32 v1, v102, v1
	v_add_f32_e32 v1, v103, v1
	v_cvt_pk_bf16_f32 v158, v98, v99
	v_cvt_pk_bf16_f32 v159, v100, v101
	ds_read_b64_tr_b16 v[206:207], v210 offset:28672
	ds_read_b64_tr_b16 v[208:209], v210 offset:29184
	v_mfma_f32_32x32x16_bf16 v[66:81], v[198:201], v[174:177], v[66:81]
	v_add_f32_e32 v1, v104, v1
	v_add_f32_e32 v1, v105, v1
	v_add_f32_e32 v1, v106, v1
	v_add_f32_e32 v1, v107, v1
	v_cvt_pk_bf16_f32 v160, v102, v103
	v_cvt_pk_bf16_f32 v161, v104, v105
	ds_read_b64_tr_b16 v[174:175], v210 offset:25600
	ds_read_b64_tr_b16 v[176:177], v210 offset:26112
	v_mfma_f32_32x32x16_bf16 v[114:129], v[202:205], v[170:173], v[114:129]
	v_add_f32_e32 v1, v108, v1
	v_add_f32_e32 v1, v109, v1
	v_add_f32_e32 v1, v110, v1
	v_add_f32_e32 v1, v111, v1
	v_cvt_pk_bf16_f32 v154, v106, v107
	v_cvt_pk_bf16_f32 v155, v108, v109
	ds_read_b64_tr_b16 v[98:99], v210 offset:29696
	ds_read_b64_tr_b16 v[100:101], v210 offset:30208
	v_mfma_f32_32x32x16_bf16 v[66:81], v[194:197], v[170:173], v[66:81]
	v_add_f32_e32 v1, v112, v1
	v_add_f32_e32 v1, v113, v1
	v_add_f32_e32 v1, v82, v1
	v_add_f32_e32 v1, v83, v1
	v_cvt_pk_bf16_f32 v156, v110, v111
	v_cvt_pk_bf16_f32 v157, v112, v113
	ds_read_b64_tr_b16 v[102:103], v210 offset:26624
	ds_read_b64_tr_b16 v[104:105], v210 offset:27136
	v_mfma_f32_32x32x16_bf16 v[114:129], v[190:193], v[166:169], v[114:129]
	v_add_f32_e32 v1, v84, v1
	v_add_f32_e32 v1, v85, v1
	v_add_f32_e32 v1, v86, v1
	v_add_f32_e32 v1, v87, v1
	v_cvt_pk_bf16_f32 v150, v82, v83
	v_cvt_pk_bf16_f32 v151, v84, v85
	ds_read_b64_tr_b16 v[106:107], v210 offset:30720
	ds_read_b64_tr_b16 v[108:109], v210 offset:31232
	v_mfma_f32_32x32x16_bf16 v[66:81], v[186:189], v[166:169], v[66:81]
	v_add_f32_e32 v1, v88, v1
	v_add_f32_e32 v1, v89, v1
	v_add_f32_e32 v1, v90, v1
	v_add_f32_e32 v1, v91, v1
	v_cvt_pk_bf16_f32 v152, v86, v87
	v_cvt_pk_bf16_f32 v153, v88, v89
	ds_read_b64_tr_b16 v[110:111], v210 offset:27648
	ds_read_b64_tr_b16 v[112:113], v210 offset:28160
	v_mfma_f32_32x32x16_bf16 v[114:129], v[182:185], v[162:165], v[114:129]
	v_add_f32_e32 v1, v92, v1
	v_add_f32_e32 v1, v93, v1
	v_add_f32_e32 v1, v94, v1
	v_add_f32_e32 v1, v95, v1
	v_cvt_pk_bf16_f32 v146, v90, v91
	v_cvt_pk_bf16_f32 v147, v92, v93
	ds_read_b64_tr_b16 v[130:131], v210 offset:31744
	ds_read_b64_tr_b16 v[132:133], v210 offset:32256
	v_mfma_f32_32x32x16_bf16 v[66:81], v[178:181], v[162:165], v[66:81]
	v_add_f32_e32 v1, v96, v1
	v_add_f32_e32 v1, v97, v1
	v_cvt_pk_bf16_f32 v148, v94, v95
	v_cvt_pk_bf16_f32 v149, v96, v97
	s_andn2_b64 vcc, exec, s[68:69]
	s_cbranch_vccnz .LBB0_1169
	s_and_b64 s[86:87], s[68:69], exec
	s_cselect_b32 s15, s54, s96
	s_ashr_i32 s33, s15, 9
	s_lshl_b32 s15, s15, 1
	s_mul_hi_i32 s87, s33, 0x18c0000
	s_mul_i32 s33, s33, 0x18c0000
	s_and_b32 s54, s15, 0x380
	s_or_b64 s[80:81], s[82:83], s[80:81]
	s_or_b32 s86, s33, s54
	s_and_b32 s15, s15, 64
	s_or_b64 s[10:11], s[80:81], s[10:11]
	s_sub_u32 s10, s15, s10
	s_subb_u32 s11, 0, s11
	v_lshl_add_u64 v[82:83], s[10:11], 1, v[220:221]
	s_sub_u32 s80, s86, s80
	v_lshl_add_u64 v[82:83], s[86:87], 1, v[82:83]
	s_mov_b64 s[10:11], 0x800
	s_subb_u32 s81, s87, s81
	v_lshl_add_u64 v[84:85], v[82:83], 0, s[10:11]
	s_add_i32 s10, s9, s55
	s_mov_b32 s11, m0
	s_mov_b32 m0, s10
	s_nop 0
	global_load_lds_dwordx4 v[84:85], off
	s_mov_b32 m0, s11
	s_lshl_b32 s10, s9, 1
	v_lshl_add_u64 v[86:87], s[80:81], 1, v[224:225]
	s_add_i32 s1, s10, s1
	s_mov_b32 s10, m0
	s_mov_b32 m0, s1
	s_nop 0
	global_load_lds_dwordx4 v[86:87], off
	s_mov_b32 m0, s10
	s_mov_b64 s[10:11], 0x80
	v_lshl_add_u64 v[84:85], v[86:87], 0, s[10:11]
	s_addk_i32 s1, 0x2000
	s_mov_b32 s10, m0
	s_mov_b32 m0, s1
	s_nop 0
	global_load_lds_dwordx4 v[84:85], off
	s_mov_b32 m0, s10
	s_mov_b64 s[10:11], 0x60800
	v_lshl_add_u64 v[84:85], v[82:83], 0, s[10:11]
	s_add_i32 s1, s8, s55
	s_mov_b32 s8, m0
	s_mov_b32 m0, s1
	s_nop 0
	global_load_lds_dwordx4 v[84:85], off
	s_mov_b32 m0, s8
	s_mov_b64 s[10:11], 0xc0800
	v_lshl_add_u64 v[82:83], v[82:83], 0, s[10:11]
	s_add_i32 s1, s4, s55
	s_mov_b32 s4, m0
	s_mov_b32 m0, s1
	s_nop 0
	global_load_lds_dwordx4 v[82:83], off
	s_mov_b32 m0, s4
.LBB0_1169:
	s_waitcnt lgkmcnt(14)
	v_mfma_f32_32x32x16_bf16 v[50:65], v[158:161], v[134:137], v[50:65]
	ds_read_b64_tr_b16 v[142:143], v210 offset:32768
	ds_read_b64_tr_b16 v[144:145], v210 offset:33280
	v_add_f32_e32 v1, v249, v1
	s_waitcnt lgkmcnt(14)
	v_mfma_f32_32x32x16_bf16 v[34:49], v[158:161], v[206:209], v[34:49]
	ds_read_b64_tr_b16 v[138:139], v210 offset:36864
	ds_read_b64_tr_b16 v[140:141], v210 offset:37376
	s_waitcnt lgkmcnt(14)
	v_mfma_f32_32x32x16_bf16 v[50:65], v[154:157], v[174:177], v[50:65]
	ds_read_b64_tr_b16 v[134:135], v210 offset:33792
	ds_read_b64_tr_b16 v[136:137], v210 offset:34304
	v_max_f32_e32 v82, v114, v115
	v_max3_f32 v83, v116, v117, v67
	v_max3_f32 v82, v82, v66, v68
	v_max3_f32 v82, v82, v69, v118
	v_max3_f32 v83, v83, v120, v121
	v_max3_f32 v82, v82, v119, v70
	v_max3_f32 v83, v83, v72, v73
	v_max3_f32 v82, v82, v71, v122
	v_max3_f32 v83, v83, v124, v125
	v_max3_f32 v82, v82, v123, v74
	v_max3_f32 v83, v83, v76, v77
	v_max3_f32 v82, v82, v75, v126
	v_max3_f32 v83, v83, v128, v129
	v_max3_f32 v82, v82, v127, v78
	v_max3_f32 v83, v83, v80, v81
	v_max3_f32 v82, v82, v79, v83
	v_mov_b32_e32 v83, v82
	s_nop 1
	v_permlane32_swap_b32_e32 v82, v83
	v_max_f32_e32 v82, v82, v83
	v_cmp_lt_f32_e32 vcc, s13, v82
	s_cmp_lg_u64 vcc, 0
	s_cselect_b64 s[80:81], -1, 0
	s_cbranch_vccnz .LBB0_1178
	s_mov_b32 s86, s0
.LBB0_1171:
	s_waitcnt lgkmcnt(14)
	v_mfma_f32_32x32x16_bf16 v[34:49], v[154:157], v[98:101], v[34:49]
	v_exp_f32_e32 v114, v114
	v_exp_f32_e32 v115, v115
	v_exp_f32_e32 v116, v116
	ds_read_b64_tr_b16 v[82:83], v210 offset:37888
	ds_read_b64_tr_b16 v[84:85], v210 offset:38400
	s_waitcnt lgkmcnt(14)
	v_mfma_f32_32x32x16_bf16 v[50:65], v[150:153], v[102:105], v[50:65]
	v_exp_f32_e32 v117, v117
	v_exp_f32_e32 v118, v118
	v_exp_f32_e32 v119, v119
	ds_read_b64_tr_b16 v[86:87], v210 offset:34816
	ds_read_b64_tr_b16 v[88:89], v210 offset:35328
	s_waitcnt lgkmcnt(14)
	v_mfma_f32_32x32x16_bf16 v[34:49], v[150:153], v[106:109], v[34:49]
	v_exp_f32_e32 v120, v120
	v_exp_f32_e32 v121, v121
	v_exp_f32_e32 v122, v122
	ds_read_b64_tr_b16 v[90:91], v210 offset:38912
	ds_read_b64_tr_b16 v[92:93], v210 offset:39424
	s_waitcnt lgkmcnt(14)
	v_mfma_f32_32x32x16_bf16 v[50:65], v[146:149], v[110:113], v[50:65]
	v_exp_f32_e32 v123, v123
	v_exp_f32_e32 v124, v124
	v_exp_f32_e32 v125, v125
	ds_read_b64_tr_b16 v[94:95], v210 offset:35840
	ds_read_b64_tr_b16 v[96:97], v210 offset:36352
	s_waitcnt lgkmcnt(14)
	v_mfma_f32_32x32x16_bf16 v[34:49], v[146:149], v[130:133], v[34:49]
	v_exp_f32_e32 v126, v126
	v_exp_f32_e32 v127, v127
	v_exp_f32_e32 v128, v128
	ds_read_b64_tr_b16 v[98:99], v210 offset:39936
	ds_read_b64_tr_b16 v[100:101], v210 offset:40448
	s_waitcnt lgkmcnt(14)
	v_mfma_f32_32x32x16_bf16 v[18:33], v[158:161], v[142:145], v[18:33]
	v_exp_f32_e32 v129, v129
	v_exp_f32_e32 v66, v66
	v_exp_f32_e32 v67, v67
	s_waitcnt lgkmcnt(12)
	v_mfma_f32_32x32x16_bf16 v[2:17], v[158:161], v[138:141], v[2:17]
	v_exp_f32_e32 v68, v68
	v_exp_f32_e32 v69, v69
	s_waitcnt lgkmcnt(10)
	v_mfma_f32_32x32x16_bf16 v[18:33], v[154:157], v[134:137], v[18:33]
	v_exp_f32_e32 v70, v70
	v_exp_f32_e32 v71, v71
	s_waitcnt lgkmcnt(8)
	v_mfma_f32_32x32x16_bf16 v[2:17], v[154:157], v[82:85], v[2:17]
	v_exp_f32_e32 v72, v72
	v_exp_f32_e32 v73, v73
	s_waitcnt lgkmcnt(6)
	v_mfma_f32_32x32x16_bf16 v[18:33], v[150:153], v[86:89], v[18:33]
	v_exp_f32_e32 v74, v74
	v_exp_f32_e32 v75, v75
	s_waitcnt lgkmcnt(4)
	v_mfma_f32_32x32x16_bf16 v[2:17], v[150:153], v[90:93], v[2:17]
	v_exp_f32_e32 v76, v76
	v_exp_f32_e32 v77, v77
	s_waitcnt lgkmcnt(2)
	v_mfma_f32_32x32x16_bf16 v[18:33], v[146:149], v[94:97], v[18:33]
	v_exp_f32_e32 v78, v78
	v_exp_f32_e32 v79, v79
	s_waitcnt lgkmcnt(0)
	v_mfma_f32_32x32x16_bf16 v[2:17], v[146:149], v[98:101], v[2:17]
	v_exp_f32_e32 v80, v80
	v_exp_f32_e32 v81, v81
	s_andn2_b64 vcc, exec, s[80:81]
	v_add_u32_e32 v82, s3, v245
	s_cbranch_vccnz .LBB0_1173
	s_waitcnt lgkmcnt(0)
	ds_read_b128 v[84:87], v82 offset:96
	ds_read_b128 v[88:91], v82 offset:64
	ds_read_b128 v[92:95], v82 offset:32
	ds_read_b128 v[96:99], v82
	s_waitcnt lgkmcnt(3)
	v_pk_mul_f32 v[62:63], v[62:63], v[84:85]
	s_waitcnt lgkmcnt(2)
	v_pk_mul_f32 v[58:59], v[58:59], v[88:89]
	s_waitcnt lgkmcnt(1)
	v_pk_mul_f32 v[54:55], v[54:55], v[92:93]
	v_pk_mul_f32 v[64:65], v[64:65], v[86:87]
	v_pk_mul_f32 v[60:61], v[60:61], v[90:91]
	v_pk_mul_f32 v[56:57], v[56:57], v[94:95]
	s_waitcnt lgkmcnt(0)
	v_pk_mul_f32 v[52:53], v[52:53], v[98:99]
	v_pk_mul_f32 v[50:51], v[50:51], v[96:97]
	v_pk_mul_f32 v[46:47], v[46:47], v[84:85]
	v_pk_mul_f32 v[42:43], v[42:43], v[88:89]
	v_pk_mul_f32 v[38:39], v[38:39], v[92:93]
	v_pk_mul_f32 v[48:49], v[48:49], v[86:87]
	v_pk_mul_f32 v[44:45], v[44:45], v[90:91]
	v_pk_mul_f32 v[40:41], v[40:41], v[94:95]
	v_pk_mul_f32 v[36:37], v[36:37], v[98:99]
	v_pk_mul_f32 v[34:35], v[34:35], v[96:97]
	v_pk_mul_f32 v[30:31], v[30:31], v[84:85]
	v_pk_mul_f32 v[26:27], v[26:27], v[88:89]
	v_pk_mul_f32 v[22:23], v[22:23], v[92:93]
	v_pk_mul_f32 v[32:33], v[32:33], v[86:87]
	v_pk_mul_f32 v[28:29], v[28:29], v[90:91]
	v_pk_mul_f32 v[24:25], v[24:25], v[94:95]
	v_pk_mul_f32 v[20:21], v[20:21], v[98:99]
	v_pk_mul_f32 v[18:19], v[18:19], v[96:97]
	v_pk_mul_f32 v[14:15], v[14:15], v[84:85]
	v_pk_mul_f32 v[10:11], v[10:11], v[88:89]
	v_pk_mul_f32 v[6:7], v[6:7], v[92:93]
	v_pk_mul_f32 v[16:17], v[16:17], v[86:87]
	v_pk_mul_f32 v[12:13], v[12:13], v[90:91]
	v_pk_mul_f32 v[8:9], v[8:9], v[94:95]
	v_pk_mul_f32 v[4:5], v[4:5], v[98:99]
	v_pk_mul_f32 v[2:3], v[2:3], v[96:97]
